# K-loop MFMA clusters: post-barrier lgkmcnt(0) loosened to counted lgkmcnt(3 or 1) with the full wait moved before the 7th MFMA; compensating nops removed so addresses stay
# baseline (speedup 1.0000x reference)
.LBB0_47:
	s_add_u32 s24, s22, 0x100
	s_addc_u32 s25, s23, 0
	s_add_i32 s46, 0, 0x10000
	v_add_u32_e32 v142, s46, v191
	ds_read_b128 v[130:133], v142
	ds_read_b128 v[134:137], v142 offset:1024
	ds_read_b128 v[138:141], v142 offset:2048
	ds_read_b128 v[142:145], v142 offset:3072
	s_cmp_eq_u32 s45, 28
	s_cselect_b32 s29, s17, s25
	s_cselect_b32 s28, s41, s24
	s_cselect_b32 s27, s15, s44
	s_cselect_b32 s26, s42, s43
	v_lshl_add_u64 v[194:195], s[22:23], 0, v[182:183]
	s_add_i32 m0, s30, 0xc000
	ds_read_b128 v[146:149], v212
	ds_read_b128 v[150:153], v212 offset:1024
	ds_read_b128 v[154:157], v212 offset:2048
	ds_read_b128 v[158:161], v212 offset:3072
	ds_read_b128 v[162:165], v212 offset:4096
	ds_read_b128 v[166:169], v212 offset:5120
	ds_read_b128 v[170:173], v212 offset:6144
	ds_read_b128 v[174:177], v212 offset:7168
	global_load_lds_dwordx4 v[194:195], off
	v_lshl_add_u64 v[194:195], s[22:23], 0, v[184:185]
	s_add_i32 m0, s30, 0xe000
	s_nop 0
	global_load_lds_dwordx4 v[194:195], off
	s_waitcnt lgkmcnt(8)
	s_barrier
	s_waitcnt lgkmcnt(3)
	s_setprio 1
	v_mfma_f32_16x16x32_bf16 v[126:129], v[130:133], v[146:149], v[126:129]
	v_mfma_f32_16x16x32_bf16 v[122:125], v[138:141], v[146:149], v[122:125]
	v_mfma_f32_16x16x32_bf16 v[110:113], v[130:133], v[154:157], v[110:113]
	v_mfma_f32_16x16x32_bf16 v[106:109], v[138:141], v[154:157], v[106:109]
	v_mfma_f32_16x16x32_bf16 v[94:97], v[130:133], v[162:165], v[94:97]
	v_mfma_f32_16x16x32_bf16 v[90:93], v[138:141], v[162:165], v[90:93]
	s_waitcnt lgkmcnt(0)
	v_mfma_f32_16x16x32_bf16 v[78:81], v[130:133], v[170:173], v[78:81]
	v_mfma_f32_16x16x32_bf16 v[74:77], v[138:141], v[170:173], v[74:77]
	v_mfma_f32_16x16x32_bf16 v[126:129], v[134:137], v[150:153], v[126:129]
	v_mfma_f32_16x16x32_bf16 v[122:125], v[142:145], v[150:153], v[122:125]
	v_mfma_f32_16x16x32_bf16 v[110:113], v[134:137], v[158:161], v[110:113]
	v_mfma_f32_16x16x32_bf16 v[106:109], v[142:145], v[158:161], v[106:109]
	v_mfma_f32_16x16x32_bf16 v[94:97], v[134:137], v[166:169], v[94:97]
	v_mfma_f32_16x16x32_bf16 v[90:93], v[142:145], v[166:169], v[90:93]
	v_mfma_f32_16x16x32_bf16 v[78:81], v[134:137], v[174:177], v[78:81]
	v_mfma_f32_16x16x32_bf16 v[74:77], v[142:145], v[174:177], v[74:77]
	s_setprio 0
	s_barrier
	s_add_i32 s47, 0, 0x14000
	s_add_i32 s22, s46, s5
	v_add_u32_e32 v206, s47, v191
	v_lshl_add_u64 v[210:211], s[26:27], 0, v[180:181]
	s_mov_b32 m0, s22
	ds_read_b128 v[194:197], v206
	ds_read_b128 v[198:201], v206 offset:1024
	ds_read_b128 v[202:205], v206 offset:2048
	ds_read_b128 v[206:209], v206 offset:3072
	global_load_lds_dwordx4 v[210:211], off
	v_lshl_add_u64 v[220:221], s[26:27], 0, v[178:179]
	s_add_i32 m0, s22, 0x2000
	s_nop 0
	global_load_lds_dwordx4 v[220:221], off
	s_barrier
	s_waitcnt lgkmcnt(1)
	s_setprio 1
	v_mfma_f32_16x16x32_bf16 v[118:121], v[194:197], v[146:149], v[118:121]
	v_mfma_f32_16x16x32_bf16 v[114:117], v[202:205], v[146:149], v[114:117]
	v_mfma_f32_16x16x32_bf16 v[102:105], v[194:197], v[154:157], v[102:105]
	v_mfma_f32_16x16x32_bf16 v[98:101], v[202:205], v[154:157], v[98:101]
	v_mfma_f32_16x16x32_bf16 v[86:89], v[194:197], v[162:165], v[86:89]
	v_mfma_f32_16x16x32_bf16 v[82:85], v[202:205], v[162:165], v[82:85]
	s_waitcnt lgkmcnt(0)
	v_mfma_f32_16x16x32_bf16 v[70:73], v[194:197], v[170:173], v[70:73]
	v_mfma_f32_16x16x32_bf16 v[66:69], v[202:205], v[170:173], v[66:69]
	v_mfma_f32_16x16x32_bf16 v[118:121], v[198:201], v[150:153], v[118:121]
	v_mfma_f32_16x16x32_bf16 v[114:117], v[206:209], v[150:153], v[114:117]
	v_mfma_f32_16x16x32_bf16 v[102:105], v[198:201], v[158:161], v[102:105]
	v_mfma_f32_16x16x32_bf16 v[98:101], v[206:209], v[158:161], v[98:101]
	v_mfma_f32_16x16x32_bf16 v[86:89], v[198:201], v[166:169], v[86:89]
	v_mfma_f32_16x16x32_bf16 v[82:85], v[206:209], v[166:169], v[82:85]
	v_mfma_f32_16x16x32_bf16 v[70:73], v[198:201], v[174:177], v[70:73]
	v_mfma_f32_16x16x32_bf16 v[66:69], v[206:209], v[174:177], v[66:69]
	s_setprio 0
	s_mov_b32 m0, s30
	v_lshl_add_u64 v[222:223], s[28:29], 0, v[180:181]
	s_barrier
	ds_read_b128 v[146:149], v212 offset:16384
	ds_read_b128 v[150:153], v212 offset:17408
	ds_read_b128 v[154:157], v212 offset:18432
	ds_read_b128 v[158:161], v212 offset:19456
	ds_read_b128 v[162:165], v212 offset:20480
	ds_read_b128 v[166:169], v212 offset:21504
	ds_read_b128 v[170:173], v212 offset:22528
	ds_read_b128 v[174:177], v212 offset:23552
	global_load_lds_dwordx4 v[222:223], off
	v_lshl_add_u64 v[224:225], s[28:29], 0, v[178:179]
	s_mov_b32 m0, s31
	s_nop 0
	global_load_lds_dwordx4 v[224:225], off
	s_barrier
	s_waitcnt lgkmcnt(3)
	s_setprio 1
	v_mfma_f32_16x16x32_bf16 v[62:65], v[130:133], v[146:149], v[62:65]
	v_mfma_f32_16x16x32_bf16 v[58:61], v[138:141], v[146:149], v[58:61]
	v_mfma_f32_16x16x32_bf16 v[46:49], v[130:133], v[154:157], v[46:49]
	v_mfma_f32_16x16x32_bf16 v[42:45], v[138:141], v[154:157], v[42:45]
	v_mfma_f32_16x16x32_bf16 v[30:33], v[130:133], v[162:165], v[30:33]
	v_mfma_f32_16x16x32_bf16 v[26:29], v[138:141], v[162:165], v[26:29]
	s_waitcnt lgkmcnt(0)
	v_mfma_f32_16x16x32_bf16 v[14:17], v[130:133], v[170:173], v[14:17]
	v_mfma_f32_16x16x32_bf16 v[10:13], v[138:141], v[170:173], v[10:13]
	v_mfma_f32_16x16x32_bf16 v[62:65], v[134:137], v[150:153], v[62:65]
	v_mfma_f32_16x16x32_bf16 v[58:61], v[142:145], v[150:153], v[58:61]
	v_mfma_f32_16x16x32_bf16 v[46:49], v[134:137], v[158:161], v[46:49]
	v_mfma_f32_16x16x32_bf16 v[42:45], v[142:145], v[158:161], v[42:45]
	v_mfma_f32_16x16x32_bf16 v[30:33], v[134:137], v[166:169], v[30:33]
	v_mfma_f32_16x16x32_bf16 v[26:29], v[142:145], v[166:169], v[26:29]
	v_mfma_f32_16x16x32_bf16 v[14:17], v[134:137], v[174:177], v[14:17]
	v_mfma_f32_16x16x32_bf16 v[10:13], v[142:145], v[174:177], v[10:13]
	s_setprio 0
	s_barrier
	s_add_u32 s22, s26, 0x80000
	s_addc_u32 s23, s27, 0
	s_add_i32 s46, s47, s5
	v_lshl_add_u64 v[130:131], s[22:23], 0, v[180:181]
	s_mov_b32 m0, s46
	s_nop 0
	global_load_lds_dwordx4 v[130:131], off
	v_lshl_add_u64 v[130:131], s[22:23], 0, v[178:179]
	s_add_i32 m0, s46, 0x2000
	s_nop 0
	global_load_lds_dwordx4 v[130:131], off
	s_waitcnt vmcnt(6)
	s_barrier
	s_setprio 1
	v_mfma_f32_16x16x32_bf16 v[54:57], v[194:197], v[146:149], v[54:57]
	v_mfma_f32_16x16x32_bf16 v[50:53], v[202:205], v[146:149], v[50:53]
	v_mfma_f32_16x16x32_bf16 v[38:41], v[194:197], v[154:157], v[38:41]
	v_mfma_f32_16x16x32_bf16 v[34:37], v[202:205], v[154:157], v[34:37]
	v_mfma_f32_16x16x32_bf16 v[22:25], v[194:197], v[162:165], v[22:25]
	v_mfma_f32_16x16x32_bf16 v[18:21], v[202:205], v[162:165], v[18:21]
	v_mfma_f32_16x16x32_bf16 v[6:9], v[194:197], v[170:173], v[6:9]
	v_mfma_f32_16x16x32_bf16 v[2:5], v[202:205], v[170:173], v[2:5]
	v_mfma_f32_16x16x32_bf16 v[54:57], v[198:201], v[150:153], v[54:57]
	v_mfma_f32_16x16x32_bf16 v[50:53], v[206:209], v[150:153], v[50:53]
	v_mfma_f32_16x16x32_bf16 v[38:41], v[198:201], v[158:161], v[38:41]
	v_mfma_f32_16x16x32_bf16 v[34:37], v[206:209], v[158:161], v[34:37]
	v_mfma_f32_16x16x32_bf16 v[22:25], v[198:201], v[166:169], v[22:25]
	v_mfma_f32_16x16x32_bf16 v[18:21], v[206:209], v[166:169], v[18:21]
	v_mfma_f32_16x16x32_bf16 v[6:9], v[198:201], v[174:177], v[6:9]
	v_mfma_f32_16x16x32_bf16 v[2:5], v[206:209], v[174:177], v[2:5]
	s_setprio 0
	s_add_i32 s46, 0, 0x18000
	v_add_u32_e32 v142, s46, v191
	s_barrier
	ds_read_b128 v[130:133], v142
	ds_read_b128 v[134:137], v142 offset:1024
	ds_read_b128 v[138:141], v142 offset:2048
	ds_read_b128 v[142:145], v142 offset:3072
	s_add_u32 s22, s28, 0x80000
	s_addc_u32 s23, s29, 0
	s_mov_b32 m0, s34
	v_lshl_add_u64 v[194:195], s[22:23], 0, v[180:181]
	ds_read_b128 v[146:149], v212 offset:32768
	ds_read_b128 v[150:153], v212 offset:33792
	ds_read_b128 v[154:157], v212 offset:34816
	ds_read_b128 v[158:161], v212 offset:35840
	ds_read_b128 v[162:165], v212 offset:36864
	ds_read_b128 v[166:169], v212 offset:37888
	ds_read_b128 v[170:173], v212 offset:38912
	ds_read_b128 v[174:177], v212 offset:39936
	global_load_lds_dwordx4 v[194:195], off
	v_lshl_add_u64 v[194:195], s[22:23], 0, v[178:179]
	s_mov_b32 m0, s35
	s_nop 0
	global_load_lds_dwordx4 v[194:195], off
	s_waitcnt lgkmcnt(8)
	s_barrier
	s_waitcnt lgkmcnt(3)
	s_setprio 1
	v_mfma_f32_16x16x32_bf16 v[126:129], v[130:133], v[146:149], v[126:129]
	v_mfma_f32_16x16x32_bf16 v[122:125], v[138:141], v[146:149], v[122:125]
	v_mfma_f32_16x16x32_bf16 v[110:113], v[130:133], v[154:157], v[110:113]
	v_mfma_f32_16x16x32_bf16 v[106:109], v[138:141], v[154:157], v[106:109]
	v_mfma_f32_16x16x32_bf16 v[94:97], v[130:133], v[162:165], v[94:97]
	v_mfma_f32_16x16x32_bf16 v[90:93], v[138:141], v[162:165], v[90:93]
	s_waitcnt lgkmcnt(0)
	v_mfma_f32_16x16x32_bf16 v[78:81], v[130:133], v[170:173], v[78:81]
	v_mfma_f32_16x16x32_bf16 v[74:77], v[138:141], v[170:173], v[74:77]
	v_mfma_f32_16x16x32_bf16 v[126:129], v[134:137], v[150:153], v[126:129]
	v_mfma_f32_16x16x32_bf16 v[122:125], v[142:145], v[150:153], v[122:125]
	v_mfma_f32_16x16x32_bf16 v[110:113], v[134:137], v[158:161], v[110:113]
	v_mfma_f32_16x16x32_bf16 v[106:109], v[142:145], v[158:161], v[106:109]
	v_mfma_f32_16x16x32_bf16 v[94:97], v[134:137], v[166:169], v[94:97]
	v_mfma_f32_16x16x32_bf16 v[90:93], v[142:145], v[166:169], v[90:93]
	v_mfma_f32_16x16x32_bf16 v[78:81], v[134:137], v[174:177], v[78:81]
	v_mfma_f32_16x16x32_bf16 v[74:77], v[142:145], v[174:177], v[74:77]
	s_setprio 0
	s_barrier
	s_add_i32 s28, 0, 0x1c000
	s_add_i32 s22, s46, s5
	v_add_u32_e32 v206, s28, v191
	v_lshl_add_u64 v[210:211], v[210:211], 0, s[6:7]
	s_mov_b32 m0, s22
	ds_read_b128 v[194:197], v206
	ds_read_b128 v[198:201], v206 offset:1024
	ds_read_b128 v[202:205], v206 offset:2048
	ds_read_b128 v[206:209], v206 offset:3072
	global_load_lds_dwordx4 v[210:211], off
	v_lshl_add_u64 v[210:211], v[220:221], 0, s[6:7]
	s_add_i32 m0, s22, 0x2000
	s_nop 0
	global_load_lds_dwordx4 v[210:211], off
	s_barrier
	s_waitcnt lgkmcnt(1)
	s_setprio 1
	v_mfma_f32_16x16x32_bf16 v[118:121], v[194:197], v[146:149], v[118:121]
	v_mfma_f32_16x16x32_bf16 v[114:117], v[202:205], v[146:149], v[114:117]
	v_mfma_f32_16x16x32_bf16 v[102:105], v[194:197], v[154:157], v[102:105]
	v_mfma_f32_16x16x32_bf16 v[98:101], v[202:205], v[154:157], v[98:101]
	v_mfma_f32_16x16x32_bf16 v[86:89], v[194:197], v[162:165], v[86:89]
	v_mfma_f32_16x16x32_bf16 v[82:85], v[202:205], v[162:165], v[82:85]
	s_waitcnt lgkmcnt(0)
	v_mfma_f32_16x16x32_bf16 v[70:73], v[194:197], v[170:173], v[70:73]
	v_mfma_f32_16x16x32_bf16 v[66:69], v[202:205], v[170:173], v[66:69]
	v_mfma_f32_16x16x32_bf16 v[118:121], v[198:201], v[150:153], v[118:121]
	v_mfma_f32_16x16x32_bf16 v[114:117], v[206:209], v[150:153], v[114:117]
	v_mfma_f32_16x16x32_bf16 v[102:105], v[198:201], v[158:161], v[102:105]
	v_mfma_f32_16x16x32_bf16 v[98:101], v[206:209], v[158:161], v[98:101]
	v_mfma_f32_16x16x32_bf16 v[86:89], v[198:201], v[166:169], v[86:89]
	v_mfma_f32_16x16x32_bf16 v[82:85], v[206:209], v[166:169], v[82:85]
	v_mfma_f32_16x16x32_bf16 v[70:73], v[198:201], v[174:177], v[70:73]
	v_mfma_f32_16x16x32_bf16 v[66:69], v[206:209], v[174:177], v[66:69]
	s_setprio 0
	s_mov_b32 m0, s36
	v_lshl_add_u64 v[210:211], v[222:223], 0, s[6:7]
	s_barrier
	ds_read_b128 v[146:149], v212 offset:49152
	ds_read_b128 v[150:153], v212 offset:50176
	ds_read_b128 v[154:157], v212 offset:51200
	ds_read_b128 v[158:161], v212 offset:52224
	ds_read_b128 v[162:165], v212 offset:53248
	ds_read_b128 v[166:169], v212 offset:54272
	ds_read_b128 v[170:173], v212 offset:55296
	ds_read_b128 v[174:177], v212 offset:56320
	global_load_lds_dwordx4 v[210:211], off
	v_lshl_add_u64 v[210:211], v[224:225], 0, s[6:7]
	s_mov_b32 m0, s37
	s_nop 0
	global_load_lds_dwordx4 v[210:211], off
	s_barrier
	s_waitcnt lgkmcnt(3)
	s_setprio 1
	v_mfma_f32_16x16x32_bf16 v[62:65], v[130:133], v[146:149], v[62:65]
	v_mfma_f32_16x16x32_bf16 v[58:61], v[138:141], v[146:149], v[58:61]
	v_mfma_f32_16x16x32_bf16 v[46:49], v[130:133], v[154:157], v[46:49]
	v_mfma_f32_16x16x32_bf16 v[42:45], v[138:141], v[154:157], v[42:45]
	v_mfma_f32_16x16x32_bf16 v[30:33], v[130:133], v[162:165], v[30:33]
	v_mfma_f32_16x16x32_bf16 v[26:29], v[138:141], v[162:165], v[26:29]
	s_waitcnt lgkmcnt(0)
	v_mfma_f32_16x16x32_bf16 v[14:17], v[130:133], v[170:173], v[14:17]
	v_mfma_f32_16x16x32_bf16 v[10:13], v[138:141], v[170:173], v[10:13]
	v_mfma_f32_16x16x32_bf16 v[62:65], v[134:137], v[150:153], v[62:65]
	v_mfma_f32_16x16x32_bf16 v[58:61], v[142:145], v[150:153], v[58:61]
	v_mfma_f32_16x16x32_bf16 v[46:49], v[134:137], v[158:161], v[46:49]
	v_mfma_f32_16x16x32_bf16 v[42:45], v[142:145], v[158:161], v[42:45]
	v_mfma_f32_16x16x32_bf16 v[30:33], v[134:137], v[166:169], v[30:33]
	v_mfma_f32_16x16x32_bf16 v[26:29], v[142:145], v[166:169], v[26:29]
	v_mfma_f32_16x16x32_bf16 v[14:17], v[134:137], v[174:177], v[14:17]
	v_mfma_f32_16x16x32_bf16 v[10:13], v[142:145], v[174:177], v[10:13]
	s_setprio 0
	s_barrier
	s_add_u32 s22, s26, 0x80080
	s_addc_u32 s23, s27, 0
	s_add_i32 s26, s28, s5
	v_lshl_add_u64 v[130:131], s[22:23], 0, v[180:181]
	s_mov_b32 m0, s26
	s_nop 0
	global_load_lds_dwordx4 v[130:131], off
	v_lshl_add_u64 v[130:131], s[22:23], 0, v[178:179]
	s_add_i32 m0, s26, 0x2000
	s_nop 0
	global_load_lds_dwordx4 v[130:131], off
	s_waitcnt vmcnt(6)
	s_barrier
	s_setprio 1
	v_mfma_f32_16x16x32_bf16 v[54:57], v[194:197], v[146:149], v[54:57]
	v_mfma_f32_16x16x32_bf16 v[50:53], v[202:205], v[146:149], v[50:53]
	v_mfma_f32_16x16x32_bf16 v[38:41], v[194:197], v[154:157], v[38:41]
	v_mfma_f32_16x16x32_bf16 v[34:37], v[202:205], v[154:157], v[34:37]
	v_mfma_f32_16x16x32_bf16 v[22:25], v[194:197], v[162:165], v[22:25]
	v_mfma_f32_16x16x32_bf16 v[18:21], v[202:205], v[162:165], v[18:21]
	v_mfma_f32_16x16x32_bf16 v[6:9], v[194:197], v[170:173], v[6:9]
	v_mfma_f32_16x16x32_bf16 v[2:5], v[202:205], v[170:173], v[2:5]
	v_mfma_f32_16x16x32_bf16 v[54:57], v[198:201], v[150:153], v[54:57]
	v_mfma_f32_16x16x32_bf16 v[50:53], v[206:209], v[150:153], v[50:53]
	v_mfma_f32_16x16x32_bf16 v[38:41], v[198:201], v[158:161], v[38:41]
	v_mfma_f32_16x16x32_bf16 v[34:37], v[206:209], v[158:161], v[34:37]
	v_mfma_f32_16x16x32_bf16 v[22:25], v[198:201], v[166:169], v[22:25]
	v_mfma_f32_16x16x32_bf16 v[18:21], v[206:209], v[166:169], v[18:21]
	v_mfma_f32_16x16x32_bf16 v[6:9], v[198:201], v[174:177], v[6:9]
	v_mfma_f32_16x16x32_bf16 v[2:5], v[206:209], v[174:177], v[2:5]
	s_setprio 0
	s_add_i32 s45, s45, 2
	s_add_u32 s43, s43, 0x100
	s_addc_u32 s44, s44, 0
	s_cmp_gt_u32 s45, 29
	s_mov_b64 s[22:23], s[24:25]
	s_barrier
	s_cbranch_scc0 .LBB0_47
	v_lshl_add_u32 v196, s39, 8, v1
	v_lshl_or_b32 v194, s40, 8, v192
	v_readlane_b32 s24, v254, 46
	v_ashrrev_i32_e32 v195, 31, v194
	v_ashrrev_i32_e32 v197, 31, v196
	v_readlane_b32 s25, v254, 47
	v_or_b32_e32 v210, 16, v196
	v_lshlrev_b64 v[130:131], 13, v[196:197]
	v_lshl_add_u64 v[198:199], v[194:195], 2, s[24:25]
	v_or_b32_e32 v206, 32, v196
	v_or_b32_e32 v202, 48, v196
	v_ashrrev_i32_e32 v211, 31, v210
	v_lshl_add_u64 v[224:225], v[198:199], 0, v[130:131]
	v_ashrrev_i32_e32 v207, 31, v206
	v_ashrrev_i32_e32 v203, 31, v202
	v_lshlrev_b64 v[130:131], 13, v[210:211]
	global_load_dwordx4 v[220:223], v[224:225], off
	global_load_dwordx4 v[236:239], v[224:225], off offset:64
	global_load_dwordx4 v[240:243], v[224:225], off offset:512
	global_load_dwordx4 v[244:247], v[224:225], off offset:576
	v_lshlrev_b64 v[132:133], 13, v[206:207]
	v_lshlrev_b64 v[134:135], 13, v[202:203]
	v_lshl_add_u64 v[208:209], v[198:199], 0, v[130:131]
	v_lshl_add_u64 v[204:205], v[198:199], 0, v[132:133]
	v_lshl_add_u64 v[200:201], v[198:199], 0, v[134:135]
	global_load_dwordx4 v[174:177], v[208:209], off
	global_load_dwordx4 v[170:173], v[208:209], off offset:64
	global_load_dwordx4 v[166:169], v[208:209], off offset:512
	global_load_dwordx4 v[162:165], v[208:209], off offset:576
	global_load_dwordx4 v[158:161], v[204:205], off
	global_load_dwordx4 v[154:157], v[204:205], off offset:64
	global_load_dwordx4 v[150:153], v[204:205], off offset:512
	global_load_dwordx4 v[146:149], v[204:205], off offset:576
	global_load_dwordx4 v[142:145], v[200:201], off
	global_load_dwordx4 v[138:141], v[200:201], off offset:64
	global_load_dwordx4 v[134:137], v[200:201], off offset:512
	global_load_dwordx4 v[130:133], v[200:201], off offset:576
	v_lshlrev_b64 v[248:249], 11, v[196:197]
	v_readlane_b32 s22, v252, 5
	v_lshl_add_u64 v[248:249], v[248:249], 0, v[194:195]
	v_readlane_b32 s23, v252, 6
	v_readlane_b32 s26, v254, 48
	v_readlane_b32 s27, v254, 49
	v_lshl_add_u64 v[248:249], v[248:249], 1, s[22:23]
	v_readlane_b32 s22, v252, 9
	v_readlane_b32 s23, v252, 10
	s_waitcnt vmcnt(0)
	v_pk_add_f32 v[128:129], v[128:129], v[222:223]
	v_pk_add_f32 v[126:127], v[126:127], v[220:221]
	v_pk_add_f32 v[122:123], v[122:123], v[236:237]
	v_pk_add_f32 v[118:119], v[118:119], v[240:241]
	global_store_dwordx4 v[224:225], v[126:129], off
	v_cvt_pk_bf16_f32 v220, v126, v127
	v_mul_f32_e32 v213, v123, v123
	v_mul_f32_e32 v127, v127, v127
	v_pk_add_f32 v[124:125], v[124:125], v[238:239]
	v_pk_add_f32 v[114:115], v[114:115], v[244:245]
	v_mul_f32_e32 v226, v119, v119
	v_fmac_f32_e32 v127, v126, v126
	v_fmac_f32_e32 v213, v122, v122
	v_pk_add_f32 v[120:121], v[120:121], v[242:243]
	v_mul_f32_e32 v235, v115, v115
	v_fmac_f32_e32 v226, v118, v118
	v_fmac_f32_e32 v127, v128, v128
	v_fmac_f32_e32 v213, v124, v124
	v_pk_add_f32 v[116:117], v[116:117], v[246:247]
	v_cvt_pk_bf16_f32 v221, v128, v129
	v_fmac_f32_e32 v235, v114, v114
	v_fmac_f32_e32 v226, v120, v120
	v_fmac_f32_e32 v127, v129, v129
	v_fmac_f32_e32 v213, v125, v125
	v_cvt_pk_bf16_f32 v222, v122, v123
	v_cvt_pk_bf16_f32 v223, v124, v125
	v_cvt_pk_bf16_f32 v236, v118, v119
	v_cvt_pk_bf16_f32 v237, v120, v121
	v_cvt_pk_bf16_f32 v238, v114, v115
	v_cvt_pk_bf16_f32 v239, v116, v117
	global_store_dwordx2 v[248:249], v[220:221], off
	global_store_dwordx4 v[224:225], v[122:125], off offset:64
	global_store_dwordx2 v[248:249], v[222:223], off offset:32
	global_store_dwordx4 v[224:225], v[118:121], off offset:512
	global_store_dwordx2 v[248:249], v[236:237], off offset:256
	global_store_dwordx4 v[224:225], v[114:117], off offset:576
	global_store_dwordx2 v[248:249], v[238:239], off offset:288
	v_fmac_f32_e32 v235, v116, v116
	v_fmac_f32_e32 v226, v121, v121
	v_add_f32_e32 v114, v127, v213
	v_fmac_f32_e32 v235, v117, v117
	v_add_f32_e32 v114, v114, v226
	v_add_f32_e32 v114, v114, v235
	v_mov_b32_e32 v115, v114
	s_nop 1
	v_permlane32_swap_b32_e32 v114, v115
	v_add_f32_e32 v116, v114, v115
	v_mov_b32_e32 v117, v116
	s_nop 1
	v_permlane16_swap_b32_e32 v116, v117
	v_lshl_add_u64 v[114:115], v[196:197], 2, s[22:23]
	s_and_saveexec_b64 s[22:23], s[10:11]
	s_cbranch_execz .LBB0_50
	v_add_f32_e32 v116, v116, v117
	global_atomic_add_f32 v[114:115], v116, off

.LBB0_163:
	s_add_u32 s14, s12, 0xfff80080
	s_addc_u32 s15, s13, -1
	s_add_i32 s47, 0, 0x10000
	v_add_u32_e32 v94, s47, v184
	ds_read_b128 v[82:85], v94
	ds_read_b128 v[86:89], v94 offset:1024
	ds_read_b128 v[90:93], v94 offset:2048
	ds_read_b128 v[94:97], v94 offset:3072
	s_cmp_eq_u32 s46, 28
	s_cselect_b32 s17, s25, s15
	s_cselect_b32 s16, s31, s14
	s_cselect_b32 s15, s23, s45
	s_cselect_b32 s14, s35, s44
	v_lshl_add_u64 v[212:213], s[12:13], 0, v[176:177]
	s_add_i32 m0, s37, 0xc000
	ds_read_b128 v[106:109], v207
	ds_read_b128 v[110:113], v207 offset:1024
	ds_read_b128 v[122:125], v207 offset:2048
	ds_read_b128 v[126:129], v207 offset:3072
	ds_read_b128 v[162:165], v207 offset:4096
	ds_read_b128 v[166:169], v207 offset:5120
	ds_read_b128 v[180:183], v207 offset:6144
	ds_read_b128 v[208:211], v207 offset:7168
	global_load_lds_dwordx4 v[212:213], off
	v_lshl_add_u64 v[212:213], s[12:13], 0, v[178:179]
	s_add_i32 m0, s37, 0xe000
	s_nop 0
	global_load_lds_dwordx4 v[212:213], off
	s_waitcnt lgkmcnt(8)
	s_barrier
	s_waitcnt lgkmcnt(3)
	s_setprio 1
	v_mfma_f32_16x16x32_bf16 v[158:161], v[82:85], v[106:109], v[158:161]
	v_mfma_f32_16x16x32_bf16 v[154:157], v[90:93], v[106:109], v[154:157]
	v_mfma_f32_16x16x32_bf16 v[150:153], v[82:85], v[122:125], v[150:153]
	v_mfma_f32_16x16x32_bf16 v[146:149], v[90:93], v[122:125], v[146:149]
	v_mfma_f32_16x16x32_bf16 v[142:145], v[82:85], v[162:165], v[142:145]
	v_mfma_f32_16x16x32_bf16 v[138:141], v[90:93], v[162:165], v[138:141]
	s_waitcnt lgkmcnt(0)
	v_mfma_f32_16x16x32_bf16 v[134:137], v[82:85], v[180:183], v[134:137]
	v_mfma_f32_16x16x32_bf16 v[130:133], v[90:93], v[180:183], v[130:133]
	v_mfma_f32_16x16x32_bf16 v[158:161], v[86:89], v[110:113], v[158:161]
	v_mfma_f32_16x16x32_bf16 v[154:157], v[94:97], v[110:113], v[154:157]
	v_mfma_f32_16x16x32_bf16 v[150:153], v[86:89], v[126:129], v[150:153]
	v_mfma_f32_16x16x32_bf16 v[146:149], v[94:97], v[126:129], v[146:149]
	v_mfma_f32_16x16x32_bf16 v[142:145], v[86:89], v[166:169], v[142:145]
	v_mfma_f32_16x16x32_bf16 v[138:141], v[94:97], v[166:169], v[138:141]
	v_mfma_f32_16x16x32_bf16 v[134:137], v[86:89], v[208:211], v[134:137]
	v_mfma_f32_16x16x32_bf16 v[130:133], v[94:97], v[208:211], v[130:133]
	s_setprio 0
	s_barrier
	s_add_i32 s50, 0, 0x14000
	v_add_u32_e32 v212, s50, v184
	s_add_i32 s47, s47, s36
	ds_read_b128 v[220:223], v212
	ds_read_b128 v[236:239], v212 offset:1024
	ds_read_b128 v[240:243], v212 offset:2048
	ds_read_b128 v[244:247], v212 offset:3072
	v_lshl_add_u64 v[212:213], s[14:15], 0, v[172:173]
	s_mov_b32 m0, s47
	v_lshl_add_u64 v[224:225], s[14:15], 0, v[170:171]
	global_load_lds_dwordx4 v[212:213], off
	s_add_i32 m0, s47, 0x2000
	s_nop 0
	global_load_lds_dwordx4 v[224:225], off
	s_barrier
	s_waitcnt lgkmcnt(1)
	s_setprio 1
	v_mfma_f32_16x16x32_bf16 v[118:121], v[220:223], v[106:109], v[118:121]
	v_mfma_f32_16x16x32_bf16 v[102:105], v[220:223], v[122:125], v[102:105]
	v_mfma_f32_16x16x32_bf16 v[98:101], v[240:243], v[122:125], v[98:101]
	v_mfma_f32_16x16x32_bf16 v[78:81], v[220:223], v[162:165], v[78:81]
	v_mfma_f32_16x16x32_bf16 v[74:77], v[240:243], v[162:165], v[74:77]
	v_mfma_f32_16x16x32_bf16 v[70:73], v[220:223], v[180:183], v[70:73]
	s_waitcnt lgkmcnt(0)
	v_mfma_f32_16x16x32_bf16 v[66:69], v[240:243], v[180:183], v[66:69]
	v_mfma_f32_16x16x32_bf16 v[118:121], v[236:239], v[110:113], v[118:121]
	v_mfma_f32_16x16x32_bf16 v[106:109], v[240:243], v[106:109], v[114:117]
	v_mfma_f32_16x16x32_bf16 v[102:105], v[236:239], v[126:129], v[102:105]
	v_mfma_f32_16x16x32_bf16 v[98:101], v[244:247], v[126:129], v[98:101]
	v_mfma_f32_16x16x32_bf16 v[78:81], v[236:239], v[166:169], v[78:81]
	v_mfma_f32_16x16x32_bf16 v[74:77], v[244:247], v[166:169], v[74:77]
	v_mfma_f32_16x16x32_bf16 v[70:73], v[236:239], v[208:211], v[70:73]
	v_mfma_f32_16x16x32_bf16 v[66:69], v[244:247], v[208:211], v[66:69]
	v_mfma_f32_16x16x32_bf16 v[106:109], v[244:247], v[110:113], v[106:109]
	s_setprio 0
	s_mov_b32 m0, s37
	v_lshl_add_u64 v[248:249], s[16:17], 0, v[172:173]
	s_barrier
	ds_read_b128 v[110:113], v207 offset:16384
	ds_read_b128 v[114:117], v207 offset:17408
	ds_read_b128 v[122:125], v207 offset:18432
	ds_read_b128 v[126:129], v207 offset:19456
	ds_read_b128 v[162:165], v207 offset:20480
	ds_read_b128 v[166:169], v207 offset:21504
	ds_read_b128 v[180:183], v207 offset:22528
	ds_read_b128 v[208:211], v207 offset:23552
	global_load_lds_dwordx4 v[248:249], off
	v_lshl_add_u64 v[250:251], s[16:17], 0, v[170:171]
	s_mov_b32 m0, s38
	s_nop 0
	global_load_lds_dwordx4 v[250:251], off
	s_barrier
	s_waitcnt lgkmcnt(3)
	s_setprio 1
	v_mfma_f32_16x16x32_bf16 v[62:65], v[82:85], v[110:113], v[62:65]
	v_mfma_f32_16x16x32_bf16 v[58:61], v[90:93], v[110:113], v[58:61]
	v_mfma_f32_16x16x32_bf16 v[54:57], v[82:85], v[122:125], v[54:57]
	v_mfma_f32_16x16x32_bf16 v[50:53], v[90:93], v[122:125], v[50:53]
	v_mfma_f32_16x16x32_bf16 v[46:49], v[82:85], v[162:165], v[46:49]
	v_mfma_f32_16x16x32_bf16 v[42:45], v[90:93], v[162:165], v[42:45]
	s_waitcnt lgkmcnt(0)
	v_mfma_f32_16x16x32_bf16 v[38:41], v[82:85], v[180:183], v[38:41]
	v_mfma_f32_16x16x32_bf16 v[34:37], v[90:93], v[180:183], v[34:37]
	v_mfma_f32_16x16x32_bf16 v[62:65], v[86:89], v[114:117], v[62:65]
	v_mfma_f32_16x16x32_bf16 v[58:61], v[94:97], v[114:117], v[58:61]
	v_mfma_f32_16x16x32_bf16 v[54:57], v[86:89], v[126:129], v[54:57]
	v_mfma_f32_16x16x32_bf16 v[50:53], v[94:97], v[126:129], v[50:53]
	v_mfma_f32_16x16x32_bf16 v[46:49], v[86:89], v[166:169], v[46:49]
	v_mfma_f32_16x16x32_bf16 v[42:45], v[94:97], v[166:169], v[42:45]
	v_mfma_f32_16x16x32_bf16 v[38:41], v[86:89], v[208:211], v[38:41]
	v_mfma_f32_16x16x32_bf16 v[34:37], v[94:97], v[208:211], v[34:37]
	s_setprio 0
	s_barrier
	s_add_u32 s48, s14, 0x80000
	s_addc_u32 s49, s15, 0
	s_add_i32 s47, s50, s36
	v_lshl_add_u64 v[82:83], s[48:49], 0, v[172:173]
	s_mov_b32 m0, s47
	s_nop 0
	global_load_lds_dwordx4 v[82:83], off
	v_lshl_add_u64 v[82:83], s[48:49], 0, v[170:171]
	s_add_i32 m0, s47, 0x2000
	s_nop 0
	global_load_lds_dwordx4 v[82:83], off
	s_waitcnt vmcnt(6)
	s_barrier
	s_setprio 1
	v_mfma_f32_16x16x32_bf16 v[30:33], v[220:223], v[110:113], v[30:33]
	v_mfma_f32_16x16x32_bf16 v[26:29], v[240:243], v[110:113], v[26:29]
	v_mfma_f32_16x16x32_bf16 v[22:25], v[220:223], v[122:125], v[22:25]
	v_mfma_f32_16x16x32_bf16 v[18:21], v[240:243], v[122:125], v[18:21]
	v_mfma_f32_16x16x32_bf16 v[14:17], v[220:223], v[162:165], v[14:17]
	v_mfma_f32_16x16x32_bf16 v[10:13], v[240:243], v[162:165], v[10:13]
	v_mfma_f32_16x16x32_bf16 v[6:9], v[220:223], v[180:183], v[6:9]
	v_mfma_f32_16x16x32_bf16 v[2:5], v[240:243], v[180:183], v[2:5]
	v_mfma_f32_16x16x32_bf16 v[30:33], v[236:239], v[114:117], v[30:33]
	v_mfma_f32_16x16x32_bf16 v[26:29], v[244:247], v[114:117], v[26:29]
	v_mfma_f32_16x16x32_bf16 v[22:25], v[236:239], v[126:129], v[22:25]
	v_mfma_f32_16x16x32_bf16 v[18:21], v[244:247], v[126:129], v[18:21]
	v_mfma_f32_16x16x32_bf16 v[14:17], v[236:239], v[166:169], v[14:17]
	v_mfma_f32_16x16x32_bf16 v[10:13], v[244:247], v[166:169], v[10:13]
	v_mfma_f32_16x16x32_bf16 v[6:9], v[236:239], v[208:211], v[6:9]
	v_mfma_f32_16x16x32_bf16 v[2:5], v[244:247], v[208:211], v[2:5]
	s_setprio 0
	s_add_i32 s47, 0, 0x18000
	v_add_u32_e32 v94, s47, v184
	s_barrier
	ds_read_b128 v[82:85], v94
	ds_read_b128 v[86:89], v94 offset:1024
	ds_read_b128 v[90:93], v94 offset:2048
	ds_read_b128 v[94:97], v94 offset:3072
	s_add_u32 s16, s16, 0x80000
	s_addc_u32 s17, s17, 0
	s_mov_b32 m0, s39
	v_lshl_add_u64 v[220:221], s[16:17], 0, v[172:173]
	ds_read_b128 v[110:113], v207 offset:32768
	ds_read_b128 v[114:117], v207 offset:33792
	ds_read_b128 v[122:125], v207 offset:34816
	ds_read_b128 v[126:129], v207 offset:35840
	ds_read_b128 v[162:165], v207 offset:36864
	ds_read_b128 v[166:169], v207 offset:37888
	ds_read_b128 v[180:183], v207 offset:38912
	ds_read_b128 v[208:211], v207 offset:39936
	global_load_lds_dwordx4 v[220:221], off
	v_lshl_add_u64 v[220:221], s[16:17], 0, v[170:171]
	s_mov_b32 m0, s40
	s_nop 0
	global_load_lds_dwordx4 v[220:221], off
	s_waitcnt lgkmcnt(8)
	s_barrier
	s_waitcnt lgkmcnt(3)
	s_setprio 1
	v_mfma_f32_16x16x32_bf16 v[158:161], v[82:85], v[110:113], v[158:161]
	v_mfma_f32_16x16x32_bf16 v[154:157], v[90:93], v[110:113], v[154:157]
	v_mfma_f32_16x16x32_bf16 v[150:153], v[82:85], v[122:125], v[150:153]
	v_mfma_f32_16x16x32_bf16 v[146:149], v[90:93], v[122:125], v[146:149]
	v_mfma_f32_16x16x32_bf16 v[142:145], v[82:85], v[162:165], v[142:145]
	v_mfma_f32_16x16x32_bf16 v[138:141], v[90:93], v[162:165], v[138:141]
	s_waitcnt lgkmcnt(0)
	v_mfma_f32_16x16x32_bf16 v[134:137], v[82:85], v[180:183], v[134:137]
	v_mfma_f32_16x16x32_bf16 v[130:133], v[90:93], v[180:183], v[130:133]
	v_mfma_f32_16x16x32_bf16 v[158:161], v[86:89], v[114:117], v[158:161]
	v_mfma_f32_16x16x32_bf16 v[154:157], v[94:97], v[114:117], v[154:157]
	v_mfma_f32_16x16x32_bf16 v[150:153], v[86:89], v[126:129], v[150:153]
	v_mfma_f32_16x16x32_bf16 v[146:149], v[94:97], v[126:129], v[146:149]
	v_mfma_f32_16x16x32_bf16 v[142:145], v[86:89], v[166:169], v[142:145]
	v_mfma_f32_16x16x32_bf16 v[138:141], v[94:97], v[166:169], v[138:141]
	v_mfma_f32_16x16x32_bf16 v[134:137], v[86:89], v[208:211], v[134:137]
	v_mfma_f32_16x16x32_bf16 v[130:133], v[94:97], v[208:211], v[130:133]
	s_setprio 0
	s_barrier
	s_add_i32 s16, 0, 0x1c000
	s_add_i32 s17, s47, s36
	v_add_u32_e32 v226, s16, v184
	v_lshl_add_u64 v[212:213], v[212:213], 0, s[6:7]
	s_mov_b32 m0, s17
	ds_read_b128 v[220:223], v226
	ds_read_b128 v[236:239], v226 offset:1024
	ds_read_b128 v[240:243], v226 offset:2048
	ds_read_b128 v[244:247], v226 offset:3072
	global_load_lds_dwordx4 v[212:213], off
	v_lshl_add_u64 v[212:213], v[224:225], 0, s[6:7]
	s_add_i32 m0, s17, 0x2000
	s_nop 0
	global_load_lds_dwordx4 v[212:213], off
	s_barrier
	s_waitcnt lgkmcnt(1)
	s_setprio 1
	v_mfma_f32_16x16x32_bf16 v[118:121], v[220:223], v[110:113], v[118:121]
	v_mfma_f32_16x16x32_bf16 v[106:109], v[240:243], v[110:113], v[106:109]
	v_mfma_f32_16x16x32_bf16 v[102:105], v[220:223], v[122:125], v[102:105]
	v_mfma_f32_16x16x32_bf16 v[98:101], v[240:243], v[122:125], v[98:101]
	v_mfma_f32_16x16x32_bf16 v[78:81], v[220:223], v[162:165], v[78:81]
	v_mfma_f32_16x16x32_bf16 v[74:77], v[240:243], v[162:165], v[74:77]
	s_waitcnt lgkmcnt(0)
	v_mfma_f32_16x16x32_bf16 v[70:73], v[220:223], v[180:183], v[70:73]
	v_mfma_f32_16x16x32_bf16 v[66:69], v[240:243], v[180:183], v[66:69]
	v_mfma_f32_16x16x32_bf16 v[118:121], v[236:239], v[114:117], v[118:121]
	v_mfma_f32_16x16x32_bf16 v[114:117], v[244:247], v[114:117], v[106:109]
	v_mfma_f32_16x16x32_bf16 v[102:105], v[236:239], v[126:129], v[102:105]
	v_mfma_f32_16x16x32_bf16 v[98:101], v[244:247], v[126:129], v[98:101]
	v_mfma_f32_16x16x32_bf16 v[78:81], v[236:239], v[166:169], v[78:81]
	v_mfma_f32_16x16x32_bf16 v[74:77], v[244:247], v[166:169], v[74:77]
	v_mfma_f32_16x16x32_bf16 v[70:73], v[236:239], v[208:211], v[70:73]
	v_mfma_f32_16x16x32_bf16 v[66:69], v[244:247], v[208:211], v[66:69]
	s_setprio 0
	s_mov_b32 m0, s41
	v_lshl_add_u64 v[212:213], v[248:249], 0, s[6:7]
	s_barrier
	ds_read_b128 v[106:109], v207 offset:49152
	ds_read_b128 v[110:113], v207 offset:50176
	ds_read_b128 v[122:125], v207 offset:51200
	ds_read_b128 v[126:129], v207 offset:52224
	ds_read_b128 v[162:165], v207 offset:53248
	ds_read_b128 v[166:169], v207 offset:54272
	ds_read_b128 v[180:183], v207 offset:55296
	ds_read_b128 v[208:211], v207 offset:56320
	global_load_lds_dwordx4 v[212:213], off
	v_lshl_add_u64 v[212:213], v[250:251], 0, s[6:7]
	s_mov_b32 m0, s42
	s_nop 0
	global_load_lds_dwordx4 v[212:213], off
	s_barrier
	s_waitcnt lgkmcnt(3)
	s_setprio 1
	v_mfma_f32_16x16x32_bf16 v[62:65], v[82:85], v[106:109], v[62:65]
	v_mfma_f32_16x16x32_bf16 v[58:61], v[90:93], v[106:109], v[58:61]
	v_mfma_f32_16x16x32_bf16 v[54:57], v[82:85], v[122:125], v[54:57]
	v_mfma_f32_16x16x32_bf16 v[50:53], v[90:93], v[122:125], v[50:53]
	v_mfma_f32_16x16x32_bf16 v[46:49], v[82:85], v[162:165], v[46:49]
	v_mfma_f32_16x16x32_bf16 v[42:45], v[90:93], v[162:165], v[42:45]
	s_waitcnt lgkmcnt(0)
	v_mfma_f32_16x16x32_bf16 v[38:41], v[82:85], v[180:183], v[38:41]
	v_mfma_f32_16x16x32_bf16 v[34:37], v[90:93], v[180:183], v[34:37]
	v_mfma_f32_16x16x32_bf16 v[62:65], v[86:89], v[110:113], v[62:65]
	v_mfma_f32_16x16x32_bf16 v[58:61], v[94:97], v[110:113], v[58:61]
	v_mfma_f32_16x16x32_bf16 v[54:57], v[86:89], v[126:129], v[54:57]
	v_mfma_f32_16x16x32_bf16 v[50:53], v[94:97], v[126:129], v[50:53]
	v_mfma_f32_16x16x32_bf16 v[46:49], v[86:89], v[166:169], v[46:49]
	v_mfma_f32_16x16x32_bf16 v[42:45], v[94:97], v[166:169], v[42:45]
	v_mfma_f32_16x16x32_bf16 v[38:41], v[86:89], v[208:211], v[38:41]
	v_mfma_f32_16x16x32_bf16 v[34:37], v[94:97], v[208:211], v[34:37]
	s_setprio 0
	s_barrier
	s_add_u32 s14, s14, 0x80080
	s_addc_u32 s15, s15, 0
	s_add_i32 s16, s16, s36
	v_lshl_add_u64 v[82:83], s[14:15], 0, v[172:173]
	s_mov_b32 m0, s16
	s_nop 0
	global_load_lds_dwordx4 v[82:83], off
	v_lshl_add_u64 v[82:83], s[14:15], 0, v[170:171]
	s_add_i32 m0, s16, 0x2000
	s_nop 0
	global_load_lds_dwordx4 v[82:83], off
	s_waitcnt vmcnt(6)
	s_barrier
	s_setprio 1
	v_mfma_f32_16x16x32_bf16 v[30:33], v[220:223], v[106:109], v[30:33]
	v_mfma_f32_16x16x32_bf16 v[26:29], v[240:243], v[106:109], v[26:29]
	v_mfma_f32_16x16x32_bf16 v[22:25], v[220:223], v[122:125], v[22:25]
	v_mfma_f32_16x16x32_bf16 v[18:21], v[240:243], v[122:125], v[18:21]
	v_mfma_f32_16x16x32_bf16 v[14:17], v[220:223], v[162:165], v[14:17]
	v_mfma_f32_16x16x32_bf16 v[10:13], v[240:243], v[162:165], v[10:13]
	v_mfma_f32_16x16x32_bf16 v[6:9], v[220:223], v[180:183], v[6:9]
	v_mfma_f32_16x16x32_bf16 v[2:5], v[240:243], v[180:183], v[2:5]
	v_mfma_f32_16x16x32_bf16 v[30:33], v[236:239], v[110:113], v[30:33]
	v_mfma_f32_16x16x32_bf16 v[26:29], v[244:247], v[110:113], v[26:29]
	v_mfma_f32_16x16x32_bf16 v[22:25], v[236:239], v[126:129], v[22:25]
	v_mfma_f32_16x16x32_bf16 v[18:21], v[244:247], v[126:129], v[18:21]
	v_mfma_f32_16x16x32_bf16 v[14:17], v[236:239], v[166:169], v[14:17]
	v_mfma_f32_16x16x32_bf16 v[10:13], v[244:247], v[166:169], v[10:13]
	v_mfma_f32_16x16x32_bf16 v[6:9], v[236:239], v[208:211], v[6:9]
	v_mfma_f32_16x16x32_bf16 v[2:5], v[244:247], v[208:211], v[2:5]
	s_setprio 0
	s_add_i32 s46, s46, 2
	s_add_u32 s12, s12, 0x100
	s_addc_u32 s13, s13, 0
	s_add_u32 s44, s44, 0x100
	s_addc_u32 s45, s45, 0
	s_cmp_gt_u32 s46, 29
	s_barrier
	s_cbranch_scc0 .LBB0_163
	s_lshl_b32 s23, s30, 8
	v_add_u32_e32 v180, s23, v1
	v_mov_b32_e32 v162, 0
	v_cndmask_b32_e64 v182, 0, 1, s[20:21]
	v_lshlrev_b32_e32 v209, 5, v180
	v_cmp_ne_u32_e64 s[16:17], 1, v182
	s_andn2_b64 vcc, exec, s[20:21]
	v_mov_b32_e32 v163, v162
	v_mov_b32_e32 v164, v162
	v_mov_b32_e32 v165, v162
	v_mov_b32_e32 v122, v162
	v_mov_b32_e32 v123, v162
	v_mov_b32_e32 v124, v162
	v_mov_b32_e32 v125, v162
	v_mov_b32_e32 v106, v162
	v_mov_b32_e32 v107, v162
	v_mov_b32_e32 v108, v162
	v_mov_b32_e32 v109, v162
	v_mov_b32_e32 v86, v162
	v_mov_b32_e32 v87, v162
	v_mov_b32_e32 v88, v162
	v_mov_b32_e32 v89, v162
	v_mov_b32_e32 v82, v162
	v_mov_b32_e32 v83, v162
	v_mov_b32_e32 v84, v162
	v_mov_b32_e32 v85, v162
	v_mov_b32_e32 v166, v162
	v_mov_b32_e32 v167, v162
	v_mov_b32_e32 v168, v162
	v_mov_b32_e32 v169, v162
	v_mov_b32_e32 v126, v162
	v_mov_b32_e32 v127, v162
	v_mov_b32_e32 v128, v162
	v_mov_b32_e32 v129, v162
	v_mov_b32_e32 v110, v162
	v_mov_b32_e32 v111, v162
	v_mov_b32_e32 v112, v162
	v_mov_b32_e32 v113, v162
	v_mov_b32_e32 v90, v162
	v_mov_b32_e32 v91, v162
	v_mov_b32_e32 v92, v162
	v_mov_b32_e32 v93, v162
	v_mov_b32_e32 v94, v162
	v_mov_b32_e32 v95, v162
	v_mov_b32_e32 v96, v162
	v_mov_b32_e32 v97, v162
	s_cbranch_vccnz .LBB0_166
	v_and_b32_e32 v82, 0x1f9e0, v209
	v_lshlrev_b32_e32 v82, 2, v82
	v_mov_b32_e32 v83, v0
	v_lshl_add_u64 v[82:83], v[174:175], 0, v[82:83]
	v_add_co_u32_e32 v84, vcc, 0x1000, v82
	s_nop 1
	v_addc_co_u32_e32 v85, vcc, 0, v83, vcc
	global_load_dwordx4 v[162:165], v[84:85], off offset:2112
	global_load_dwordx4 v[166:169], v[84:85], off offset:2048
	global_load_dwordx4 v[126:129], v[82:83], off
	global_load_dwordx4 v[122:125], v[82:83], off offset:64
	global_load_dwordx4 v[110:113], v[82:83], off offset:2048
	global_load_dwordx4 v[106:109], v[82:83], off offset:2112
	global_load_dwordx4 v[90:93], v[84:85], off
	global_load_dwordx4 v[86:89], v[84:85], off offset:64
	s_waitcnt vmcnt(0)
	v_mov_b32_e32 v82, v162
	v_mov_b32_e32 v83, v163
	v_mov_b32_e32 v84, v164
	v_mov_b32_e32 v85, v165
	v_mov_b32_e32 v94, v166
	v_mov_b32_e32 v95, v167
	v_mov_b32_e32 v96, v168
	v_mov_b32_e32 v97, v169

.LBB0_253:
	s_add_u32 s24, s22, 0x100
	s_addc_u32 s25, s23, 0
	s_add_i32 s46, 0, 0x10000
	v_add_u32_e32 v142, s46, v191
	ds_read_b128 v[130:133], v142
	ds_read_b128 v[134:137], v142 offset:1024
	ds_read_b128 v[138:141], v142 offset:2048
	ds_read_b128 v[142:145], v142 offset:3072
	s_cmp_eq_u32 s45, 28
	s_cselect_b32 s29, s17, s25
	s_cselect_b32 s28, s41, s24
	s_cselect_b32 s27, s15, s44
	s_cselect_b32 s26, s42, s43
	v_lshl_add_u64 v[194:195], s[22:23], 0, v[182:183]
	s_add_i32 m0, s30, 0xc000
	ds_read_b128 v[146:149], v212
	ds_read_b128 v[150:153], v212 offset:1024
	ds_read_b128 v[154:157], v212 offset:2048
	ds_read_b128 v[158:161], v212 offset:3072
	ds_read_b128 v[162:165], v212 offset:4096
	ds_read_b128 v[166:169], v212 offset:5120
	ds_read_b128 v[170:173], v212 offset:6144
	ds_read_b128 v[174:177], v212 offset:7168
	global_load_lds_dwordx4 v[194:195], off
	v_lshl_add_u64 v[194:195], s[22:23], 0, v[184:185]
	s_add_i32 m0, s30, 0xe000
	s_nop 0
	global_load_lds_dwordx4 v[194:195], off
	s_waitcnt lgkmcnt(8)
	s_barrier
	s_waitcnt lgkmcnt(3)
	s_setprio 1
	v_mfma_f32_16x16x32_bf16 v[126:129], v[130:133], v[146:149], v[126:129]
	v_mfma_f32_16x16x32_bf16 v[122:125], v[138:141], v[146:149], v[122:125]
	v_mfma_f32_16x16x32_bf16 v[110:113], v[130:133], v[154:157], v[110:113]
	v_mfma_f32_16x16x32_bf16 v[106:109], v[138:141], v[154:157], v[106:109]
	v_mfma_f32_16x16x32_bf16 v[94:97], v[130:133], v[162:165], v[94:97]
	v_mfma_f32_16x16x32_bf16 v[90:93], v[138:141], v[162:165], v[90:93]
	s_waitcnt lgkmcnt(0)
	v_mfma_f32_16x16x32_bf16 v[78:81], v[130:133], v[170:173], v[78:81]
	v_mfma_f32_16x16x32_bf16 v[74:77], v[138:141], v[170:173], v[74:77]
	v_mfma_f32_16x16x32_bf16 v[126:129], v[134:137], v[150:153], v[126:129]
	v_mfma_f32_16x16x32_bf16 v[122:125], v[142:145], v[150:153], v[122:125]
	v_mfma_f32_16x16x32_bf16 v[110:113], v[134:137], v[158:161], v[110:113]
	v_mfma_f32_16x16x32_bf16 v[106:109], v[142:145], v[158:161], v[106:109]
	v_mfma_f32_16x16x32_bf16 v[94:97], v[134:137], v[166:169], v[94:97]
	v_mfma_f32_16x16x32_bf16 v[90:93], v[142:145], v[166:169], v[90:93]
	v_mfma_f32_16x16x32_bf16 v[78:81], v[134:137], v[174:177], v[78:81]
	v_mfma_f32_16x16x32_bf16 v[74:77], v[142:145], v[174:177], v[74:77]
	s_setprio 0
	s_barrier
	s_add_i32 s47, 0, 0x14000
	s_add_i32 s22, s46, s5
	v_add_u32_e32 v206, s47, v191
	v_lshl_add_u64 v[210:211], s[26:27], 0, v[180:181]
	s_mov_b32 m0, s22
	ds_read_b128 v[194:197], v206
	ds_read_b128 v[198:201], v206 offset:1024
	ds_read_b128 v[202:205], v206 offset:2048
	ds_read_b128 v[206:209], v206 offset:3072
	global_load_lds_dwordx4 v[210:211], off
	v_lshl_add_u64 v[220:221], s[26:27], 0, v[178:179]
	s_add_i32 m0, s22, 0x2000
	s_nop 0
	global_load_lds_dwordx4 v[220:221], off
	s_barrier
	s_waitcnt lgkmcnt(1)
	s_setprio 1
	v_mfma_f32_16x16x32_bf16 v[118:121], v[194:197], v[146:149], v[118:121]
	v_mfma_f32_16x16x32_bf16 v[114:117], v[202:205], v[146:149], v[114:117]
	v_mfma_f32_16x16x32_bf16 v[102:105], v[194:197], v[154:157], v[102:105]
	v_mfma_f32_16x16x32_bf16 v[98:101], v[202:205], v[154:157], v[98:101]
	v_mfma_f32_16x16x32_bf16 v[86:89], v[194:197], v[162:165], v[86:89]
	v_mfma_f32_16x16x32_bf16 v[82:85], v[202:205], v[162:165], v[82:85]
	s_waitcnt lgkmcnt(0)
	v_mfma_f32_16x16x32_bf16 v[70:73], v[194:197], v[170:173], v[70:73]
	v_mfma_f32_16x16x32_bf16 v[66:69], v[202:205], v[170:173], v[66:69]
	v_mfma_f32_16x16x32_bf16 v[118:121], v[198:201], v[150:153], v[118:121]
	v_mfma_f32_16x16x32_bf16 v[114:117], v[206:209], v[150:153], v[114:117]
	v_mfma_f32_16x16x32_bf16 v[102:105], v[198:201], v[158:161], v[102:105]
	v_mfma_f32_16x16x32_bf16 v[98:101], v[206:209], v[158:161], v[98:101]
	v_mfma_f32_16x16x32_bf16 v[86:89], v[198:201], v[166:169], v[86:89]
	v_mfma_f32_16x16x32_bf16 v[82:85], v[206:209], v[166:169], v[82:85]
	v_mfma_f32_16x16x32_bf16 v[70:73], v[198:201], v[174:177], v[70:73]
	v_mfma_f32_16x16x32_bf16 v[66:69], v[206:209], v[174:177], v[66:69]
	s_setprio 0
	s_mov_b32 m0, s30
	v_lshl_add_u64 v[222:223], s[28:29], 0, v[180:181]
	s_barrier
	ds_read_b128 v[146:149], v212 offset:16384
	ds_read_b128 v[150:153], v212 offset:17408
	ds_read_b128 v[154:157], v212 offset:18432
	ds_read_b128 v[158:161], v212 offset:19456
	ds_read_b128 v[162:165], v212 offset:20480
	ds_read_b128 v[166:169], v212 offset:21504
	ds_read_b128 v[170:173], v212 offset:22528
	ds_read_b128 v[174:177], v212 offset:23552
	global_load_lds_dwordx4 v[222:223], off
	v_lshl_add_u64 v[224:225], s[28:29], 0, v[178:179]
	s_mov_b32 m0, s31
	s_nop 0
	global_load_lds_dwordx4 v[224:225], off
	s_barrier
	s_waitcnt lgkmcnt(3)
	s_setprio 1
	v_mfma_f32_16x16x32_bf16 v[62:65], v[130:133], v[146:149], v[62:65]
	v_mfma_f32_16x16x32_bf16 v[58:61], v[138:141], v[146:149], v[58:61]
	v_mfma_f32_16x16x32_bf16 v[46:49], v[130:133], v[154:157], v[46:49]
	v_mfma_f32_16x16x32_bf16 v[42:45], v[138:141], v[154:157], v[42:45]
	v_mfma_f32_16x16x32_bf16 v[30:33], v[130:133], v[162:165], v[30:33]
	v_mfma_f32_16x16x32_bf16 v[26:29], v[138:141], v[162:165], v[26:29]
	s_waitcnt lgkmcnt(0)
	v_mfma_f32_16x16x32_bf16 v[14:17], v[130:133], v[170:173], v[14:17]
	v_mfma_f32_16x16x32_bf16 v[10:13], v[138:141], v[170:173], v[10:13]
	v_mfma_f32_16x16x32_bf16 v[62:65], v[134:137], v[150:153], v[62:65]
	v_mfma_f32_16x16x32_bf16 v[58:61], v[142:145], v[150:153], v[58:61]
	v_mfma_f32_16x16x32_bf16 v[46:49], v[134:137], v[158:161], v[46:49]
	v_mfma_f32_16x16x32_bf16 v[42:45], v[142:145], v[158:161], v[42:45]
	v_mfma_f32_16x16x32_bf16 v[30:33], v[134:137], v[166:169], v[30:33]
	v_mfma_f32_16x16x32_bf16 v[26:29], v[142:145], v[166:169], v[26:29]
	v_mfma_f32_16x16x32_bf16 v[14:17], v[134:137], v[174:177], v[14:17]
	v_mfma_f32_16x16x32_bf16 v[10:13], v[142:145], v[174:177], v[10:13]
	s_setprio 0
	s_barrier
	s_add_u32 s22, s26, 0x80000
	s_addc_u32 s23, s27, 0
	s_add_i32 s46, s47, s5
	v_lshl_add_u64 v[130:131], s[22:23], 0, v[180:181]
	s_mov_b32 m0, s46
	s_nop 0
	global_load_lds_dwordx4 v[130:131], off
	v_lshl_add_u64 v[130:131], s[22:23], 0, v[178:179]
	s_add_i32 m0, s46, 0x2000
	s_nop 0
	global_load_lds_dwordx4 v[130:131], off
	s_waitcnt vmcnt(6)
	s_barrier
	s_setprio 1
	v_mfma_f32_16x16x32_bf16 v[54:57], v[194:197], v[146:149], v[54:57]
	v_mfma_f32_16x16x32_bf16 v[50:53], v[202:205], v[146:149], v[50:53]
	v_mfma_f32_16x16x32_bf16 v[38:41], v[194:197], v[154:157], v[38:41]
	v_mfma_f32_16x16x32_bf16 v[34:37], v[202:205], v[154:157], v[34:37]
	v_mfma_f32_16x16x32_bf16 v[22:25], v[194:197], v[162:165], v[22:25]
	v_mfma_f32_16x16x32_bf16 v[18:21], v[202:205], v[162:165], v[18:21]
	v_mfma_f32_16x16x32_bf16 v[6:9], v[194:197], v[170:173], v[6:9]
	v_mfma_f32_16x16x32_bf16 v[2:5], v[202:205], v[170:173], v[2:5]
	v_mfma_f32_16x16x32_bf16 v[54:57], v[198:201], v[150:153], v[54:57]
	v_mfma_f32_16x16x32_bf16 v[50:53], v[206:209], v[150:153], v[50:53]
	v_mfma_f32_16x16x32_bf16 v[38:41], v[198:201], v[158:161], v[38:41]
	v_mfma_f32_16x16x32_bf16 v[34:37], v[206:209], v[158:161], v[34:37]
	v_mfma_f32_16x16x32_bf16 v[22:25], v[198:201], v[166:169], v[22:25]
	v_mfma_f32_16x16x32_bf16 v[18:21], v[206:209], v[166:169], v[18:21]
	v_mfma_f32_16x16x32_bf16 v[6:9], v[198:201], v[174:177], v[6:9]
	v_mfma_f32_16x16x32_bf16 v[2:5], v[206:209], v[174:177], v[2:5]
	s_setprio 0
	s_add_i32 s46, 0, 0x18000
	v_add_u32_e32 v142, s46, v191
	s_barrier
	ds_read_b128 v[130:133], v142
	ds_read_b128 v[134:137], v142 offset:1024
	ds_read_b128 v[138:141], v142 offset:2048
	ds_read_b128 v[142:145], v142 offset:3072
	s_add_u32 s22, s28, 0x80000
	s_addc_u32 s23, s29, 0
	s_mov_b32 m0, s34
	v_lshl_add_u64 v[194:195], s[22:23], 0, v[180:181]
	ds_read_b128 v[146:149], v212 offset:32768
	ds_read_b128 v[150:153], v212 offset:33792
	ds_read_b128 v[154:157], v212 offset:34816
	ds_read_b128 v[158:161], v212 offset:35840
	ds_read_b128 v[162:165], v212 offset:36864
	ds_read_b128 v[166:169], v212 offset:37888
	ds_read_b128 v[170:173], v212 offset:38912
	ds_read_b128 v[174:177], v212 offset:39936
	global_load_lds_dwordx4 v[194:195], off
	v_lshl_add_u64 v[194:195], s[22:23], 0, v[178:179]
	s_mov_b32 m0, s35
	s_nop 0
	global_load_lds_dwordx4 v[194:195], off
	s_waitcnt lgkmcnt(8)
	s_barrier
	s_waitcnt lgkmcnt(3)
	s_setprio 1
	v_mfma_f32_16x16x32_bf16 v[126:129], v[130:133], v[146:149], v[126:129]
	v_mfma_f32_16x16x32_bf16 v[122:125], v[138:141], v[146:149], v[122:125]
	v_mfma_f32_16x16x32_bf16 v[110:113], v[130:133], v[154:157], v[110:113]
	v_mfma_f32_16x16x32_bf16 v[106:109], v[138:141], v[154:157], v[106:109]
	v_mfma_f32_16x16x32_bf16 v[94:97], v[130:133], v[162:165], v[94:97]
	v_mfma_f32_16x16x32_bf16 v[90:93], v[138:141], v[162:165], v[90:93]
	s_waitcnt lgkmcnt(0)
	v_mfma_f32_16x16x32_bf16 v[78:81], v[130:133], v[170:173], v[78:81]
	v_mfma_f32_16x16x32_bf16 v[74:77], v[138:141], v[170:173], v[74:77]
	v_mfma_f32_16x16x32_bf16 v[126:129], v[134:137], v[150:153], v[126:129]
	v_mfma_f32_16x16x32_bf16 v[122:125], v[142:145], v[150:153], v[122:125]
	v_mfma_f32_16x16x32_bf16 v[110:113], v[134:137], v[158:161], v[110:113]
	v_mfma_f32_16x16x32_bf16 v[106:109], v[142:145], v[158:161], v[106:109]
	v_mfma_f32_16x16x32_bf16 v[94:97], v[134:137], v[166:169], v[94:97]
	v_mfma_f32_16x16x32_bf16 v[90:93], v[142:145], v[166:169], v[90:93]
	v_mfma_f32_16x16x32_bf16 v[78:81], v[134:137], v[174:177], v[78:81]
	v_mfma_f32_16x16x32_bf16 v[74:77], v[142:145], v[174:177], v[74:77]
	s_setprio 0
	s_barrier
	s_add_i32 s28, 0, 0x1c000
	s_add_i32 s22, s46, s5
	v_add_u32_e32 v206, s28, v191
	v_lshl_add_u64 v[210:211], v[210:211], 0, s[6:7]
	s_mov_b32 m0, s22
	ds_read_b128 v[194:197], v206
	ds_read_b128 v[198:201], v206 offset:1024
	ds_read_b128 v[202:205], v206 offset:2048
	ds_read_b128 v[206:209], v206 offset:3072
	global_load_lds_dwordx4 v[210:211], off
	v_lshl_add_u64 v[210:211], v[220:221], 0, s[6:7]
	s_add_i32 m0, s22, 0x2000
	s_nop 0
	global_load_lds_dwordx4 v[210:211], off
	s_barrier
	s_waitcnt lgkmcnt(1)
	s_setprio 1
	v_mfma_f32_16x16x32_bf16 v[118:121], v[194:197], v[146:149], v[118:121]
	v_mfma_f32_16x16x32_bf16 v[114:117], v[202:205], v[146:149], v[114:117]
	v_mfma_f32_16x16x32_bf16 v[102:105], v[194:197], v[154:157], v[102:105]
	v_mfma_f32_16x16x32_bf16 v[98:101], v[202:205], v[154:157], v[98:101]
	v_mfma_f32_16x16x32_bf16 v[86:89], v[194:197], v[162:165], v[86:89]
	v_mfma_f32_16x16x32_bf16 v[82:85], v[202:205], v[162:165], v[82:85]
	s_waitcnt lgkmcnt(0)
	v_mfma_f32_16x16x32_bf16 v[70:73], v[194:197], v[170:173], v[70:73]
	v_mfma_f32_16x16x32_bf16 v[66:69], v[202:205], v[170:173], v[66:69]
	v_mfma_f32_16x16x32_bf16 v[118:121], v[198:201], v[150:153], v[118:121]
	v_mfma_f32_16x16x32_bf16 v[114:117], v[206:209], v[150:153], v[114:117]
	v_mfma_f32_16x16x32_bf16 v[102:105], v[198:201], v[158:161], v[102:105]
	v_mfma_f32_16x16x32_bf16 v[98:101], v[206:209], v[158:161], v[98:101]
	v_mfma_f32_16x16x32_bf16 v[86:89], v[198:201], v[166:169], v[86:89]
	v_mfma_f32_16x16x32_bf16 v[82:85], v[206:209], v[166:169], v[82:85]
	v_mfma_f32_16x16x32_bf16 v[70:73], v[198:201], v[174:177], v[70:73]
	v_mfma_f32_16x16x32_bf16 v[66:69], v[206:209], v[174:177], v[66:69]
	s_setprio 0
	s_mov_b32 m0, s36
	v_lshl_add_u64 v[210:211], v[222:223], 0, s[6:7]
	s_barrier
	ds_read_b128 v[146:149], v212 offset:49152
	ds_read_b128 v[150:153], v212 offset:50176
	ds_read_b128 v[154:157], v212 offset:51200
	ds_read_b128 v[158:161], v212 offset:52224
	ds_read_b128 v[162:165], v212 offset:53248
	ds_read_b128 v[166:169], v212 offset:54272
	ds_read_b128 v[170:173], v212 offset:55296
	ds_read_b128 v[174:177], v212 offset:56320
	global_load_lds_dwordx4 v[210:211], off
	v_lshl_add_u64 v[210:211], v[224:225], 0, s[6:7]
	s_mov_b32 m0, s37
	s_nop 0
	global_load_lds_dwordx4 v[210:211], off
	s_barrier
	s_waitcnt lgkmcnt(3)
	s_setprio 1
	v_mfma_f32_16x16x32_bf16 v[62:65], v[130:133], v[146:149], v[62:65]
	v_mfma_f32_16x16x32_bf16 v[58:61], v[138:141], v[146:149], v[58:61]
	v_mfma_f32_16x16x32_bf16 v[46:49], v[130:133], v[154:157], v[46:49]
	v_mfma_f32_16x16x32_bf16 v[42:45], v[138:141], v[154:157], v[42:45]
	v_mfma_f32_16x16x32_bf16 v[30:33], v[130:133], v[162:165], v[30:33]
	v_mfma_f32_16x16x32_bf16 v[26:29], v[138:141], v[162:165], v[26:29]
	s_waitcnt lgkmcnt(0)
	v_mfma_f32_16x16x32_bf16 v[14:17], v[130:133], v[170:173], v[14:17]
	v_mfma_f32_16x16x32_bf16 v[10:13], v[138:141], v[170:173], v[10:13]
	v_mfma_f32_16x16x32_bf16 v[62:65], v[134:137], v[150:153], v[62:65]
	v_mfma_f32_16x16x32_bf16 v[58:61], v[142:145], v[150:153], v[58:61]
	v_mfma_f32_16x16x32_bf16 v[46:49], v[134:137], v[158:161], v[46:49]
	v_mfma_f32_16x16x32_bf16 v[42:45], v[142:145], v[158:161], v[42:45]
	v_mfma_f32_16x16x32_bf16 v[30:33], v[134:137], v[166:169], v[30:33]
	v_mfma_f32_16x16x32_bf16 v[26:29], v[142:145], v[166:169], v[26:29]
	v_mfma_f32_16x16x32_bf16 v[14:17], v[134:137], v[174:177], v[14:17]
	v_mfma_f32_16x16x32_bf16 v[10:13], v[142:145], v[174:177], v[10:13]
	s_setprio 0
	s_barrier
	s_add_u32 s22, s26, 0x80080
	s_addc_u32 s23, s27, 0
	s_add_i32 s26, s28, s5
	v_lshl_add_u64 v[130:131], s[22:23], 0, v[180:181]
	s_mov_b32 m0, s26
	s_nop 0
	global_load_lds_dwordx4 v[130:131], off
	v_lshl_add_u64 v[130:131], s[22:23], 0, v[178:179]
	s_add_i32 m0, s26, 0x2000
	s_nop 0
	global_load_lds_dwordx4 v[130:131], off
	s_waitcnt vmcnt(6)
	s_barrier
	s_setprio 1
	v_mfma_f32_16x16x32_bf16 v[54:57], v[194:197], v[146:149], v[54:57]
	v_mfma_f32_16x16x32_bf16 v[50:53], v[202:205], v[146:149], v[50:53]
	v_mfma_f32_16x16x32_bf16 v[38:41], v[194:197], v[154:157], v[38:41]
	v_mfma_f32_16x16x32_bf16 v[34:37], v[202:205], v[154:157], v[34:37]
	v_mfma_f32_16x16x32_bf16 v[22:25], v[194:197], v[162:165], v[22:25]
	v_mfma_f32_16x16x32_bf16 v[18:21], v[202:205], v[162:165], v[18:21]
	v_mfma_f32_16x16x32_bf16 v[6:9], v[194:197], v[170:173], v[6:9]
	v_mfma_f32_16x16x32_bf16 v[2:5], v[202:205], v[170:173], v[2:5]
	v_mfma_f32_16x16x32_bf16 v[54:57], v[198:201], v[150:153], v[54:57]
	v_mfma_f32_16x16x32_bf16 v[50:53], v[206:209], v[150:153], v[50:53]
	v_mfma_f32_16x16x32_bf16 v[38:41], v[198:201], v[158:161], v[38:41]
	v_mfma_f32_16x16x32_bf16 v[34:37], v[206:209], v[158:161], v[34:37]
	v_mfma_f32_16x16x32_bf16 v[22:25], v[198:201], v[166:169], v[22:25]
	v_mfma_f32_16x16x32_bf16 v[18:21], v[206:209], v[166:169], v[18:21]
	v_mfma_f32_16x16x32_bf16 v[6:9], v[198:201], v[174:177], v[6:9]
	v_mfma_f32_16x16x32_bf16 v[2:5], v[206:209], v[174:177], v[2:5]
	s_setprio 0
	s_add_i32 s45, s45, 2
	s_add_u32 s43, s43, 0x100
	s_addc_u32 s44, s44, 0
	s_cmp_gt_u32 s45, 29
	s_mov_b64 s[22:23], s[24:25]
	s_barrier
	s_cbranch_scc0 .LBB0_253
	v_lshl_add_u32 v196, s39, 8, v1
	v_lshl_or_b32 v194, s40, 8, v192
	v_readlane_b32 s24, v254, 46
	v_ashrrev_i32_e32 v195, 31, v194
	v_ashrrev_i32_e32 v197, 31, v196
	v_readlane_b32 s25, v254, 47
	v_or_b32_e32 v210, 16, v196
	v_lshlrev_b64 v[130:131], 13, v[196:197]
	v_lshl_add_u64 v[198:199], v[194:195], 2, s[24:25]
	v_or_b32_e32 v206, 32, v196
	v_or_b32_e32 v202, 48, v196
	v_ashrrev_i32_e32 v211, 31, v210
	v_lshl_add_u64 v[224:225], v[198:199], 0, v[130:131]
	v_ashrrev_i32_e32 v207, 31, v206
	v_ashrrev_i32_e32 v203, 31, v202
	v_lshlrev_b64 v[130:131], 13, v[210:211]
	global_load_dwordx4 v[220:223], v[224:225], off
	global_load_dwordx4 v[236:239], v[224:225], off offset:64
	global_load_dwordx4 v[240:243], v[224:225], off offset:512
	global_load_dwordx4 v[244:247], v[224:225], off offset:576
	v_lshlrev_b64 v[132:133], 13, v[206:207]
	v_lshlrev_b64 v[134:135], 13, v[202:203]
	v_lshl_add_u64 v[208:209], v[198:199], 0, v[130:131]
	v_lshl_add_u64 v[204:205], v[198:199], 0, v[132:133]
	v_lshl_add_u64 v[200:201], v[198:199], 0, v[134:135]
	global_load_dwordx4 v[174:177], v[208:209], off
	global_load_dwordx4 v[170:173], v[208:209], off offset:64
	global_load_dwordx4 v[166:169], v[208:209], off offset:512
	global_load_dwordx4 v[162:165], v[208:209], off offset:576
	global_load_dwordx4 v[158:161], v[204:205], off
	global_load_dwordx4 v[154:157], v[204:205], off offset:64
	global_load_dwordx4 v[150:153], v[204:205], off offset:512
	global_load_dwordx4 v[146:149], v[204:205], off offset:576
	global_load_dwordx4 v[142:145], v[200:201], off
	global_load_dwordx4 v[138:141], v[200:201], off offset:64
	global_load_dwordx4 v[134:137], v[200:201], off offset:512
	global_load_dwordx4 v[130:133], v[200:201], off offset:576
	v_lshlrev_b64 v[248:249], 11, v[196:197]
	v_readlane_b32 s22, v252, 5
	v_lshl_add_u64 v[248:249], v[248:249], 0, v[194:195]
	v_readlane_b32 s23, v252, 6
	v_readlane_b32 s26, v254, 48
	v_readlane_b32 s27, v254, 49
	v_lshl_add_u64 v[248:249], v[248:249], 1, s[22:23]
	v_readlane_b32 s22, v252, 40
	v_readlane_b32 s23, v252, 41
	s_waitcnt vmcnt(0)
	v_pk_add_f32 v[128:129], v[128:129], v[222:223]
	v_pk_add_f32 v[126:127], v[126:127], v[220:221]
	v_pk_add_f32 v[122:123], v[122:123], v[236:237]
	v_pk_add_f32 v[118:119], v[118:119], v[240:241]
	global_store_dwordx4 v[224:225], v[126:129], off
	v_cvt_pk_bf16_f32 v220, v126, v127
	v_mul_f32_e32 v213, v123, v123
	v_mul_f32_e32 v127, v127, v127
	v_pk_add_f32 v[124:125], v[124:125], v[238:239]
	v_pk_add_f32 v[114:115], v[114:115], v[244:245]
	v_mul_f32_e32 v226, v119, v119
	v_fmac_f32_e32 v127, v126, v126
	v_fmac_f32_e32 v213, v122, v122
	v_pk_add_f32 v[120:121], v[120:121], v[242:243]
	v_mul_f32_e32 v235, v115, v115
	v_fmac_f32_e32 v226, v118, v118
	v_fmac_f32_e32 v127, v128, v128
	v_fmac_f32_e32 v213, v124, v124
	v_pk_add_f32 v[116:117], v[116:117], v[246:247]
	v_cvt_pk_bf16_f32 v221, v128, v129
	v_fmac_f32_e32 v235, v114, v114
	v_fmac_f32_e32 v226, v120, v120
	v_fmac_f32_e32 v127, v129, v129
	v_fmac_f32_e32 v213, v125, v125
	v_cvt_pk_bf16_f32 v222, v122, v123
	v_cvt_pk_bf16_f32 v223, v124, v125
	v_cvt_pk_bf16_f32 v236, v118, v119
	v_cvt_pk_bf16_f32 v237, v120, v121
	v_cvt_pk_bf16_f32 v238, v114, v115
	v_cvt_pk_bf16_f32 v239, v116, v117
	global_store_dwordx2 v[248:249], v[220:221], off
	global_store_dwordx4 v[224:225], v[122:125], off offset:64
	global_store_dwordx2 v[248:249], v[222:223], off offset:32
	global_store_dwordx4 v[224:225], v[118:121], off offset:512
	global_store_dwordx2 v[248:249], v[236:237], off offset:256
	global_store_dwordx4 v[224:225], v[114:117], off offset:576
	global_store_dwordx2 v[248:249], v[238:239], off offset:288
	v_fmac_f32_e32 v235, v116, v116
	v_fmac_f32_e32 v226, v121, v121
	v_add_f32_e32 v114, v127, v213
	v_fmac_f32_e32 v235, v117, v117
	v_add_f32_e32 v114, v114, v226
	v_add_f32_e32 v114, v114, v235
	v_mov_b32_e32 v115, v114
	s_nop 1
	v_permlane32_swap_b32_e32 v114, v115
	v_add_f32_e32 v116, v114, v115
	v_mov_b32_e32 v117, v116
	s_nop 1
	v_permlane16_swap_b32_e32 v116, v117
	v_lshl_add_u64 v[114:115], v[196:197], 2, s[22:23]
	s_and_saveexec_b64 s[22:23], s[10:11]
	s_cbranch_execz .LBB0_256
	v_add_f32_e32 v116, v116, v117
	global_atomic_add_f32 v[114:115], v116, off

.LBB0_383:
	s_add_u32 s14, s12, 0xfff80080
	s_addc_u32 s15, s13, -1
	s_add_i32 s43, 0, 0x10000
	v_add_u32_e32 v142, s43, v144
	ds_read_b128 v[162:165], v142
	ds_read_b128 v[166:169], v142 offset:1024
	ds_read_b128 v[170:173], v142 offset:2048
	ds_read_b128 v[174:177], v142 offset:3072
	s_cmp_eq_u32 s42, 28
	s_cselect_b32 s25, s4, s15
	s_cselect_b32 s24, s19, s14
	s_cselect_b32 s15, s17, s41
	s_cselect_b32 s14, s39, s40
	v_lshl_add_u64 v[142:143], s[12:13], 0, v[138:139]
	s_add_i32 m0, s29, 0xc000
	ds_read_b128 v[178:181], v161
	ds_read_b128 v[182:185], v161 offset:1024
	ds_read_b128 v[194:197], v161 offset:2048
	ds_read_b128 v[198:201], v161 offset:3072
	ds_read_b128 v[202:205], v161 offset:4096
	ds_read_b128 v[206:209], v161 offset:5120
	ds_read_b128 v[210:213], v161 offset:6144
	ds_read_b128 v[236:239], v161 offset:7168
	global_load_lds_dwordx4 v[142:143], off
	v_lshl_add_u64 v[142:143], s[12:13], 0, v[140:141]
	s_add_i32 m0, s29, 0xe000
	s_nop 0
	global_load_lds_dwordx4 v[142:143], off
	s_waitcnt lgkmcnt(8)
	s_barrier
	s_waitcnt lgkmcnt(3)
	s_setprio 1
	v_mfma_f32_16x16x32_bf16 v[126:129], v[162:165], v[178:181], v[126:129]
	v_mfma_f32_16x16x32_bf16 v[122:125], v[170:173], v[178:181], v[122:125]
	v_mfma_f32_16x16x32_bf16 v[110:113], v[162:165], v[194:197], v[110:113]
	v_mfma_f32_16x16x32_bf16 v[106:109], v[170:173], v[194:197], v[106:109]
	v_mfma_f32_16x16x32_bf16 v[94:97], v[162:165], v[202:205], v[94:97]
	v_mfma_f32_16x16x32_bf16 v[90:93], v[170:173], v[202:205], v[90:93]
	s_waitcnt lgkmcnt(0)
	v_mfma_f32_16x16x32_bf16 v[78:81], v[162:165], v[210:213], v[78:81]
	v_mfma_f32_16x16x32_bf16 v[74:77], v[170:173], v[210:213], v[74:77]
	v_mfma_f32_16x16x32_bf16 v[126:129], v[166:169], v[182:185], v[126:129]
	v_mfma_f32_16x16x32_bf16 v[122:125], v[174:177], v[182:185], v[122:125]
	v_mfma_f32_16x16x32_bf16 v[110:113], v[166:169], v[198:201], v[110:113]
	v_mfma_f32_16x16x32_bf16 v[106:109], v[174:177], v[198:201], v[106:109]
	v_mfma_f32_16x16x32_bf16 v[94:97], v[166:169], v[206:209], v[94:97]
	v_mfma_f32_16x16x32_bf16 v[90:93], v[174:177], v[206:209], v[90:93]
	v_mfma_f32_16x16x32_bf16 v[78:81], v[166:169], v[236:239], v[78:81]
	v_mfma_f32_16x16x32_bf16 v[74:77], v[174:177], v[236:239], v[74:77]
	s_setprio 0
	s_barrier
	s_add_i32 s46, 0, 0x14000
	v_add_u32_e32 v142, s46, v144
	s_add_i32 s43, s43, s28
	ds_read_b128 v[240:243], v142
	ds_read_b128 v[244:247], v142 offset:1024
	ds_read_b128 v[248:251], v142 offset:2048
	ds_read_b128 v[220:223], v142 offset:3072
	v_lshl_add_u64 v[142:143], s[14:15], 0, v[134:135]
	s_mov_b32 m0, s43
	v_lshl_add_u64 v[224:225], s[14:15], 0, v[130:131]
	global_load_lds_dwordx4 v[142:143], off
	s_add_i32 m0, s43, 0x2000
	s_nop 0
	global_load_lds_dwordx4 v[224:225], off
	s_barrier
	s_waitcnt lgkmcnt(1)
	s_setprio 1
	v_mfma_f32_16x16x32_bf16 v[118:121], v[240:243], v[178:181], v[118:121]
	v_mfma_f32_16x16x32_bf16 v[114:117], v[248:251], v[178:181], v[114:117]
	v_mfma_f32_16x16x32_bf16 v[102:105], v[240:243], v[194:197], v[102:105]
	v_mfma_f32_16x16x32_bf16 v[98:101], v[248:251], v[194:197], v[98:101]
	v_mfma_f32_16x16x32_bf16 v[86:89], v[240:243], v[202:205], v[86:89]
	v_mfma_f32_16x16x32_bf16 v[82:85], v[248:251], v[202:205], v[82:85]
	s_waitcnt lgkmcnt(0)
	v_mfma_f32_16x16x32_bf16 v[70:73], v[240:243], v[210:213], v[70:73]
	v_mfma_f32_16x16x32_bf16 v[66:69], v[248:251], v[210:213], v[66:69]
	v_mfma_f32_16x16x32_bf16 v[118:121], v[244:247], v[182:185], v[118:121]
	v_mfma_f32_16x16x32_bf16 v[114:117], v[220:223], v[182:185], v[114:117]
	v_mfma_f32_16x16x32_bf16 v[102:105], v[244:247], v[198:201], v[102:105]
	v_mfma_f32_16x16x32_bf16 v[98:101], v[220:223], v[198:201], v[98:101]
	v_mfma_f32_16x16x32_bf16 v[86:89], v[244:247], v[206:209], v[86:89]
	v_mfma_f32_16x16x32_bf16 v[82:85], v[220:223], v[206:209], v[82:85]
	v_mfma_f32_16x16x32_bf16 v[70:73], v[244:247], v[236:239], v[70:73]
	v_mfma_f32_16x16x32_bf16 v[66:69], v[220:223], v[236:239], v[66:69]
	s_setprio 0
	s_mov_b32 m0, s29
	v_lshl_add_u64 v[146:147], s[24:25], 0, v[136:137]
	s_barrier
	ds_read_b128 v[178:181], v161 offset:16384
	ds_read_b128 v[182:185], v161 offset:17408
	ds_read_b128 v[194:197], v161 offset:18432
	ds_read_b128 v[198:201], v161 offset:19456
	ds_read_b128 v[202:205], v161 offset:20480
	ds_read_b128 v[206:209], v161 offset:21504
	ds_read_b128 v[210:213], v161 offset:22528
	ds_read_b128 v[236:239], v161 offset:23552
	global_load_lds_dwordx4 v[146:147], off
	v_lshl_add_u64 v[148:149], s[24:25], 0, v[132:133]
	s_mov_b32 m0, s30
	s_nop 0
	global_load_lds_dwordx4 v[148:149], off
	s_barrier
	s_waitcnt lgkmcnt(3)
	s_setprio 1
	v_mfma_f32_16x16x32_bf16 v[62:65], v[162:165], v[178:181], v[62:65]
	v_mfma_f32_16x16x32_bf16 v[58:61], v[170:173], v[178:181], v[58:61]
	v_mfma_f32_16x16x32_bf16 v[46:49], v[162:165], v[194:197], v[46:49]
	v_mfma_f32_16x16x32_bf16 v[42:45], v[170:173], v[194:197], v[42:45]
	v_mfma_f32_16x16x32_bf16 v[30:33], v[162:165], v[202:205], v[30:33]
	v_mfma_f32_16x16x32_bf16 v[26:29], v[170:173], v[202:205], v[26:29]
	s_waitcnt lgkmcnt(0)
	v_mfma_f32_16x16x32_bf16 v[14:17], v[162:165], v[210:213], v[14:17]
	v_mfma_f32_16x16x32_bf16 v[10:13], v[170:173], v[210:213], v[10:13]
	v_mfma_f32_16x16x32_bf16 v[62:65], v[166:169], v[182:185], v[62:65]
	v_mfma_f32_16x16x32_bf16 v[58:61], v[174:177], v[182:185], v[58:61]
	v_mfma_f32_16x16x32_bf16 v[46:49], v[166:169], v[198:201], v[46:49]
	v_mfma_f32_16x16x32_bf16 v[42:45], v[174:177], v[198:201], v[42:45]
	v_mfma_f32_16x16x32_bf16 v[30:33], v[166:169], v[206:209], v[30:33]
	v_mfma_f32_16x16x32_bf16 v[26:29], v[174:177], v[206:209], v[26:29]
	v_mfma_f32_16x16x32_bf16 v[14:17], v[166:169], v[236:239], v[14:17]
	v_mfma_f32_16x16x32_bf16 v[10:13], v[174:177], v[236:239], v[10:13]
	s_setprio 0
	s_barrier
	s_add_u32 s44, s14, 0x80000
	s_addc_u32 s45, s15, 0
	s_add_i32 s43, s46, s28
	v_lshl_add_u64 v[162:163], s[44:45], 0, v[134:135]
	s_mov_b32 m0, s43
	s_nop 0
	global_load_lds_dwordx4 v[162:163], off
	v_lshl_add_u64 v[162:163], s[44:45], 0, v[130:131]
	s_add_i32 m0, s43, 0x2000
	s_nop 0
	global_load_lds_dwordx4 v[162:163], off
	s_waitcnt vmcnt(6)
	s_barrier
	s_setprio 1
	v_mfma_f32_16x16x32_bf16 v[54:57], v[240:243], v[178:181], v[54:57]
	v_mfma_f32_16x16x32_bf16 v[50:53], v[248:251], v[178:181], v[50:53]
	v_mfma_f32_16x16x32_bf16 v[38:41], v[240:243], v[194:197], v[38:41]
	v_mfma_f32_16x16x32_bf16 v[34:37], v[248:251], v[194:197], v[34:37]
	v_mfma_f32_16x16x32_bf16 v[22:25], v[240:243], v[202:205], v[22:25]
	v_mfma_f32_16x16x32_bf16 v[18:21], v[248:251], v[202:205], v[18:21]
	v_mfma_f32_16x16x32_bf16 v[6:9], v[240:243], v[210:213], v[6:9]
	v_mfma_f32_16x16x32_bf16 v[2:5], v[248:251], v[210:213], v[2:5]
	v_mfma_f32_16x16x32_bf16 v[54:57], v[244:247], v[182:185], v[54:57]
	v_mfma_f32_16x16x32_bf16 v[50:53], v[220:223], v[182:185], v[50:53]
	v_mfma_f32_16x16x32_bf16 v[38:41], v[244:247], v[198:201], v[38:41]
	v_mfma_f32_16x16x32_bf16 v[34:37], v[220:223], v[198:201], v[34:37]
	v_mfma_f32_16x16x32_bf16 v[22:25], v[244:247], v[206:209], v[22:25]
	v_mfma_f32_16x16x32_bf16 v[18:21], v[220:223], v[206:209], v[18:21]
	v_mfma_f32_16x16x32_bf16 v[6:9], v[244:247], v[236:239], v[6:9]
	v_mfma_f32_16x16x32_bf16 v[2:5], v[220:223], v[236:239], v[2:5]
	s_setprio 0
	s_add_i32 s43, 0, 0x18000
	v_add_u32_e32 v174, s43, v144
	s_barrier
	ds_read_b128 v[162:165], v174
	ds_read_b128 v[166:169], v174 offset:1024
	ds_read_b128 v[170:173], v174 offset:2048
	ds_read_b128 v[174:177], v174 offset:3072
	s_add_u32 s24, s24, 0x80000
	s_addc_u32 s25, s25, 0
	s_mov_b32 m0, s31
	v_lshl_add_u64 v[236:237], s[24:25], 0, v[136:137]
	ds_read_b128 v[178:181], v161 offset:32768
	ds_read_b128 v[182:185], v161 offset:33792
	ds_read_b128 v[194:197], v161 offset:34816
	ds_read_b128 v[198:201], v161 offset:35840
	ds_read_b128 v[202:205], v161 offset:36864
	ds_read_b128 v[206:209], v161 offset:37888
	ds_read_b128 v[210:213], v161 offset:38912
	ds_read_b128 v[220:223], v161 offset:39936
	global_load_lds_dwordx4 v[236:237], off
	v_lshl_add_u64 v[236:237], s[24:25], 0, v[132:133]
	s_mov_b32 m0, s34
	s_nop 0
	global_load_lds_dwordx4 v[236:237], off
	s_waitcnt lgkmcnt(8)
	s_barrier
	s_waitcnt lgkmcnt(3)
	s_setprio 1
	v_mfma_f32_16x16x32_bf16 v[126:129], v[162:165], v[178:181], v[126:129]
	v_mfma_f32_16x16x32_bf16 v[122:125], v[170:173], v[178:181], v[122:125]
	v_mfma_f32_16x16x32_bf16 v[110:113], v[162:165], v[194:197], v[110:113]
	v_mfma_f32_16x16x32_bf16 v[106:109], v[170:173], v[194:197], v[106:109]
	v_mfma_f32_16x16x32_bf16 v[94:97], v[162:165], v[202:205], v[94:97]
	v_mfma_f32_16x16x32_bf16 v[90:93], v[170:173], v[202:205], v[90:93]
	s_waitcnt lgkmcnt(0)
	v_mfma_f32_16x16x32_bf16 v[78:81], v[162:165], v[210:213], v[78:81]
	v_mfma_f32_16x16x32_bf16 v[74:77], v[170:173], v[210:213], v[74:77]
	v_mfma_f32_16x16x32_bf16 v[126:129], v[166:169], v[182:185], v[126:129]
	v_mfma_f32_16x16x32_bf16 v[122:125], v[174:177], v[182:185], v[122:125]
	v_mfma_f32_16x16x32_bf16 v[110:113], v[166:169], v[198:201], v[110:113]
	v_mfma_f32_16x16x32_bf16 v[106:109], v[174:177], v[198:201], v[106:109]
	v_mfma_f32_16x16x32_bf16 v[94:97], v[166:169], v[206:209], v[94:97]
	v_mfma_f32_16x16x32_bf16 v[90:93], v[174:177], v[206:209], v[90:93]
	v_mfma_f32_16x16x32_bf16 v[78:81], v[166:169], v[220:223], v[78:81]
	v_mfma_f32_16x16x32_bf16 v[74:77], v[174:177], v[220:223], v[74:77]
	s_setprio 0
	s_barrier
	s_add_i32 s24, 0, 0x1c000
	s_add_i32 s25, s43, s28
	v_add_u32_e32 v248, s24, v144
	v_lshl_add_u64 v[142:143], v[142:143], 0, s[6:7]
	s_mov_b32 m0, s25
	ds_read_b128 v[236:239], v248
	ds_read_b128 v[240:243], v248 offset:1024
	ds_read_b128 v[244:247], v248 offset:2048
	ds_read_b128 v[248:251], v248 offset:3072
	global_load_lds_dwordx4 v[142:143], off
	v_lshl_add_u64 v[142:143], v[224:225], 0, s[6:7]
	s_add_i32 m0, s25, 0x2000
	s_nop 0
	global_load_lds_dwordx4 v[142:143], off
	s_barrier
	s_waitcnt lgkmcnt(1)
	s_setprio 1
	v_mfma_f32_16x16x32_bf16 v[118:121], v[236:239], v[178:181], v[118:121]
	v_mfma_f32_16x16x32_bf16 v[114:117], v[244:247], v[178:181], v[114:117]
	v_mfma_f32_16x16x32_bf16 v[102:105], v[236:239], v[194:197], v[102:105]
	v_mfma_f32_16x16x32_bf16 v[98:101], v[244:247], v[194:197], v[98:101]
	v_mfma_f32_16x16x32_bf16 v[86:89], v[236:239], v[202:205], v[86:89]
	v_mfma_f32_16x16x32_bf16 v[82:85], v[244:247], v[202:205], v[82:85]
	s_waitcnt lgkmcnt(0)
	v_mfma_f32_16x16x32_bf16 v[70:73], v[236:239], v[210:213], v[70:73]
	v_mfma_f32_16x16x32_bf16 v[66:69], v[244:247], v[210:213], v[66:69]
	v_mfma_f32_16x16x32_bf16 v[118:121], v[240:243], v[182:185], v[118:121]
	v_mfma_f32_16x16x32_bf16 v[114:117], v[248:251], v[182:185], v[114:117]
	v_mfma_f32_16x16x32_bf16 v[102:105], v[240:243], v[198:201], v[102:105]
	v_mfma_f32_16x16x32_bf16 v[98:101], v[248:251], v[198:201], v[98:101]
	v_mfma_f32_16x16x32_bf16 v[86:89], v[240:243], v[206:209], v[86:89]
	v_mfma_f32_16x16x32_bf16 v[82:85], v[248:251], v[206:209], v[82:85]
	v_mfma_f32_16x16x32_bf16 v[70:73], v[240:243], v[220:223], v[70:73]
	v_mfma_f32_16x16x32_bf16 v[66:69], v[248:251], v[220:223], v[66:69]
	s_setprio 0
	s_mov_b32 m0, s35
	v_lshl_add_u64 v[142:143], v[146:147], 0, s[6:7]
	s_barrier
	ds_read_b128 v[178:181], v161 offset:49152
	ds_read_b128 v[182:185], v161 offset:50176
	ds_read_b128 v[194:197], v161 offset:51200
	ds_read_b128 v[198:201], v161 offset:52224
	ds_read_b128 v[202:205], v161 offset:53248
	ds_read_b128 v[206:209], v161 offset:54272
	ds_read_b128 v[210:213], v161 offset:55296
	ds_read_b128 v[220:223], v161 offset:56320
	global_load_lds_dwordx4 v[142:143], off
	v_lshl_add_u64 v[142:143], v[148:149], 0, s[6:7]
	s_mov_b32 m0, s36
	s_nop 0
	global_load_lds_dwordx4 v[142:143], off
	s_barrier
	s_waitcnt lgkmcnt(3)
	s_setprio 1
	v_mfma_f32_16x16x32_bf16 v[62:65], v[162:165], v[178:181], v[62:65]
	v_mfma_f32_16x16x32_bf16 v[58:61], v[170:173], v[178:181], v[58:61]
	v_mfma_f32_16x16x32_bf16 v[46:49], v[162:165], v[194:197], v[46:49]
	v_mfma_f32_16x16x32_bf16 v[42:45], v[170:173], v[194:197], v[42:45]
	v_mfma_f32_16x16x32_bf16 v[30:33], v[162:165], v[202:205], v[30:33]
	v_mfma_f32_16x16x32_bf16 v[26:29], v[170:173], v[202:205], v[26:29]
	s_waitcnt lgkmcnt(0)
	v_mfma_f32_16x16x32_bf16 v[14:17], v[162:165], v[210:213], v[14:17]
	v_mfma_f32_16x16x32_bf16 v[10:13], v[170:173], v[210:213], v[10:13]
	v_mfma_f32_16x16x32_bf16 v[62:65], v[166:169], v[182:185], v[62:65]
	v_mfma_f32_16x16x32_bf16 v[58:61], v[174:177], v[182:185], v[58:61]
	v_mfma_f32_16x16x32_bf16 v[46:49], v[166:169], v[198:201], v[46:49]
	v_mfma_f32_16x16x32_bf16 v[42:45], v[174:177], v[198:201], v[42:45]
	v_mfma_f32_16x16x32_bf16 v[30:33], v[166:169], v[206:209], v[30:33]
	v_mfma_f32_16x16x32_bf16 v[26:29], v[174:177], v[206:209], v[26:29]
	v_mfma_f32_16x16x32_bf16 v[14:17], v[166:169], v[220:223], v[14:17]
	v_mfma_f32_16x16x32_bf16 v[10:13], v[174:177], v[220:223], v[10:13]
	s_setprio 0
	s_barrier
	s_add_u32 s14, s14, 0x80080
	s_addc_u32 s15, s15, 0
	s_add_i32 s24, s24, s28
	v_lshl_add_u64 v[142:143], s[14:15], 0, v[134:135]
	s_mov_b32 m0, s24
	s_nop 0
	global_load_lds_dwordx4 v[142:143], off
	v_lshl_add_u64 v[142:143], s[14:15], 0, v[130:131]
	s_add_i32 m0, s24, 0x2000
	s_nop 0
	global_load_lds_dwordx4 v[142:143], off
	s_waitcnt vmcnt(6)
	s_barrier
	s_setprio 1
	v_mfma_f32_16x16x32_bf16 v[54:57], v[236:239], v[178:181], v[54:57]
	v_mfma_f32_16x16x32_bf16 v[50:53], v[244:247], v[178:181], v[50:53]
	v_mfma_f32_16x16x32_bf16 v[38:41], v[236:239], v[194:197], v[38:41]
	v_mfma_f32_16x16x32_bf16 v[34:37], v[244:247], v[194:197], v[34:37]
	v_mfma_f32_16x16x32_bf16 v[22:25], v[236:239], v[202:205], v[22:25]
	v_mfma_f32_16x16x32_bf16 v[18:21], v[244:247], v[202:205], v[18:21]
	v_mfma_f32_16x16x32_bf16 v[6:9], v[236:239], v[210:213], v[6:9]
	v_mfma_f32_16x16x32_bf16 v[2:5], v[244:247], v[210:213], v[2:5]
	v_mfma_f32_16x16x32_bf16 v[54:57], v[240:243], v[182:185], v[54:57]
	v_mfma_f32_16x16x32_bf16 v[50:53], v[248:251], v[182:185], v[50:53]
	v_mfma_f32_16x16x32_bf16 v[38:41], v[240:243], v[198:201], v[38:41]
	v_mfma_f32_16x16x32_bf16 v[34:37], v[248:251], v[198:201], v[34:37]
	v_mfma_f32_16x16x32_bf16 v[22:25], v[240:243], v[206:209], v[22:25]
	v_mfma_f32_16x16x32_bf16 v[18:21], v[248:251], v[206:209], v[18:21]
	v_mfma_f32_16x16x32_bf16 v[6:9], v[240:243], v[220:223], v[6:9]
	v_mfma_f32_16x16x32_bf16 v[2:5], v[248:251], v[220:223], v[2:5]
	s_setprio 0
	s_add_i32 s42, s42, 2
	s_add_u32 s12, s12, 0x100
	s_addc_u32 s13, s13, 0
	s_add_u32 s40, s40, 0x100
	s_addc_u32 s41, s41, 0
	s_cmp_gt_u32 s42, 29
	s_barrier
	s_cbranch_scc0 .LBB0_383
	s_lshl_b32 s4, s38, 8
	s_cmp_lg_u32 s38, s26
	v_add_u32_e32 v142, s4, v1
	s_cselect_b64 s[24:25], -1, 0
	s_mov_b64 s[12:13], -1
	s_and_b64 vcc, exec, s[24:25]
	v_ashrrev_i32_e32 v143, 31, v142
	s_cbranch_vccz .LBB0_386
	v_readlane_b32 s12, v252, 46
	v_readlane_b32 s13, v252, 47
	s_nop 1
	v_lshl_add_u64 v[162:163], v[142:143], 2, s[12:13]
	global_load_dword v146, v[162:163], off
	s_mov_b64 s[12:13], 0
	s_waitcnt vmcnt(0)
	v_fmamk_f32 v146, v146, 0x3a000000, v215
	v_mul_f32_e32 v147, 0x4b800000, v146
	v_cmp_gt_f32_e32 vcc, s65, v146
	s_nop 1
	v_cndmask_b32_e32 v146, v146, v147, vcc
	v_rsq_f32_e32 v146, v146
	s_nop 0
	v_mul_f32_e32 v147, 0x45800000, v146
	v_cndmask_b32_e32 v162, v146, v147, vcc

.LBB0_695:
	s_add_u32 s24, s22, 0x100
	s_addc_u32 s25, s23, 0
	s_add_i32 s48, 0, 0x10000
	v_add_u32_e32 v142, s48, v191
	ds_read_b128 v[130:133], v142
	ds_read_b128 v[134:137], v142 offset:1024
	ds_read_b128 v[138:141], v142 offset:2048
	ds_read_b128 v[142:145], v142 offset:3072
	s_cmpk_eq_i32 s47, 0x54
	s_cselect_b32 s29, s15, s25
	s_cselect_b32 s28, s14, s24
	s_cselect_b32 s27, s17, s46
	s_cselect_b32 s26, s16, s45
	v_lshl_add_u64 v[178:179], s[22:23], 0, v[198:199]
	s_add_i32 m0, s34, 0xc000
	ds_read_b128 v[146:149], v236
	ds_read_b128 v[150:153], v236 offset:1024
	ds_read_b128 v[154:157], v236 offset:2048
	ds_read_b128 v[158:161], v236 offset:3072
	ds_read_b128 v[162:165], v236 offset:4096
	ds_read_b128 v[166:169], v236 offset:5120
	ds_read_b128 v[170:173], v236 offset:6144
	ds_read_b128 v[174:177], v236 offset:7168
	global_load_lds_dwordx4 v[178:179], off
	v_lshl_add_u64 v[178:179], s[22:23], 0, v[200:201]
	s_add_i32 m0, s34, 0xe000
	s_nop 0
	global_load_lds_dwordx4 v[178:179], off
	s_waitcnt lgkmcnt(8)
	s_barrier
	s_waitcnt lgkmcnt(3)
	s_setprio 1
	v_mfma_f32_16x16x32_bf16 v[126:129], v[130:133], v[146:149], v[126:129]
	v_mfma_f32_16x16x32_bf16 v[122:125], v[138:141], v[146:149], v[122:125]
	v_mfma_f32_16x16x32_bf16 v[110:113], v[130:133], v[154:157], v[110:113]
	v_mfma_f32_16x16x32_bf16 v[106:109], v[138:141], v[154:157], v[106:109]
	v_mfma_f32_16x16x32_bf16 v[94:97], v[130:133], v[162:165], v[94:97]
	v_mfma_f32_16x16x32_bf16 v[90:93], v[138:141], v[162:165], v[90:93]
	s_waitcnt lgkmcnt(0)
	v_mfma_f32_16x16x32_bf16 v[78:81], v[130:133], v[170:173], v[78:81]
	v_mfma_f32_16x16x32_bf16 v[74:77], v[138:141], v[170:173], v[74:77]
	v_mfma_f32_16x16x32_bf16 v[126:129], v[134:137], v[150:153], v[126:129]
	v_mfma_f32_16x16x32_bf16 v[122:125], v[142:145], v[150:153], v[122:125]
	v_mfma_f32_16x16x32_bf16 v[110:113], v[134:137], v[158:161], v[110:113]
	v_mfma_f32_16x16x32_bf16 v[106:109], v[142:145], v[158:161], v[106:109]
	v_mfma_f32_16x16x32_bf16 v[94:97], v[134:137], v[166:169], v[94:97]
	v_mfma_f32_16x16x32_bf16 v[90:93], v[142:145], v[166:169], v[90:93]
	v_mfma_f32_16x16x32_bf16 v[78:81], v[134:137], v[174:177], v[78:81]
	v_mfma_f32_16x16x32_bf16 v[74:77], v[142:145], v[174:177], v[74:77]
	s_setprio 0
	s_barrier
	s_add_i32 s49, 0, 0x14000
	s_add_i32 s22, s48, s5
	v_add_u32_e32 v206, s49, v191
	v_lshl_add_u64 v[210:211], s[26:27], 0, v[196:197]
	s_mov_b32 m0, s22
	ds_read_b128 v[178:181], v206
	ds_read_b128 v[182:185], v206 offset:1024
	ds_read_b128 v[202:205], v206 offset:2048
	ds_read_b128 v[206:209], v206 offset:3072
	global_load_lds_dwordx4 v[210:211], off
	v_lshl_add_u64 v[212:213], s[26:27], 0, v[194:195]
	s_add_i32 m0, s22, 0x2000
	s_nop 0
	global_load_lds_dwordx4 v[212:213], off
	s_barrier
	s_waitcnt lgkmcnt(1)
	s_setprio 1
	v_mfma_f32_16x16x32_bf16 v[118:121], v[178:181], v[146:149], v[118:121]
	v_mfma_f32_16x16x32_bf16 v[114:117], v[202:205], v[146:149], v[114:117]
	v_mfma_f32_16x16x32_bf16 v[102:105], v[178:181], v[154:157], v[102:105]
	v_mfma_f32_16x16x32_bf16 v[98:101], v[202:205], v[154:157], v[98:101]
	v_mfma_f32_16x16x32_bf16 v[86:89], v[178:181], v[162:165], v[86:89]
	v_mfma_f32_16x16x32_bf16 v[82:85], v[202:205], v[162:165], v[82:85]
	s_waitcnt lgkmcnt(0)
	v_mfma_f32_16x16x32_bf16 v[70:73], v[178:181], v[170:173], v[70:73]
	v_mfma_f32_16x16x32_bf16 v[66:69], v[202:205], v[170:173], v[66:69]
	v_mfma_f32_16x16x32_bf16 v[118:121], v[182:185], v[150:153], v[118:121]
	v_mfma_f32_16x16x32_bf16 v[114:117], v[206:209], v[150:153], v[114:117]
	v_mfma_f32_16x16x32_bf16 v[102:105], v[182:185], v[158:161], v[102:105]
	v_mfma_f32_16x16x32_bf16 v[98:101], v[206:209], v[158:161], v[98:101]
	v_mfma_f32_16x16x32_bf16 v[86:89], v[182:185], v[166:169], v[86:89]
	v_mfma_f32_16x16x32_bf16 v[82:85], v[206:209], v[166:169], v[82:85]
	v_mfma_f32_16x16x32_bf16 v[70:73], v[182:185], v[174:177], v[70:73]
	v_mfma_f32_16x16x32_bf16 v[66:69], v[206:209], v[174:177], v[66:69]
	s_setprio 0
	s_mov_b32 m0, s34
	v_lshl_add_u64 v[220:221], s[28:29], 0, v[196:197]
	s_barrier
	ds_read_b128 v[146:149], v236 offset:16384
	ds_read_b128 v[150:153], v236 offset:17408
	ds_read_b128 v[154:157], v236 offset:18432
	ds_read_b128 v[158:161], v236 offset:19456
	ds_read_b128 v[162:165], v236 offset:20480
	ds_read_b128 v[166:169], v236 offset:21504
	ds_read_b128 v[170:173], v236 offset:22528
	ds_read_b128 v[174:177], v236 offset:23552
	global_load_lds_dwordx4 v[220:221], off
	v_lshl_add_u64 v[222:223], s[28:29], 0, v[194:195]
	s_mov_b32 m0, s35
	s_nop 0
	global_load_lds_dwordx4 v[222:223], off
	s_barrier
	s_waitcnt lgkmcnt(3)
	s_setprio 1
	v_mfma_f32_16x16x32_bf16 v[62:65], v[130:133], v[146:149], v[62:65]
	v_mfma_f32_16x16x32_bf16 v[58:61], v[138:141], v[146:149], v[58:61]
	v_mfma_f32_16x16x32_bf16 v[46:49], v[130:133], v[154:157], v[46:49]
	v_mfma_f32_16x16x32_bf16 v[42:45], v[138:141], v[154:157], v[42:45]
	v_mfma_f32_16x16x32_bf16 v[30:33], v[130:133], v[162:165], v[30:33]
	v_mfma_f32_16x16x32_bf16 v[26:29], v[138:141], v[162:165], v[26:29]
	s_waitcnt lgkmcnt(0)
	v_mfma_f32_16x16x32_bf16 v[14:17], v[130:133], v[170:173], v[14:17]
	v_mfma_f32_16x16x32_bf16 v[10:13], v[138:141], v[170:173], v[10:13]
	v_mfma_f32_16x16x32_bf16 v[62:65], v[134:137], v[150:153], v[62:65]
	v_mfma_f32_16x16x32_bf16 v[58:61], v[142:145], v[150:153], v[58:61]
	v_mfma_f32_16x16x32_bf16 v[46:49], v[134:137], v[158:161], v[46:49]
	v_mfma_f32_16x16x32_bf16 v[42:45], v[142:145], v[158:161], v[42:45]
	v_mfma_f32_16x16x32_bf16 v[30:33], v[134:137], v[166:169], v[30:33]
	v_mfma_f32_16x16x32_bf16 v[26:29], v[142:145], v[166:169], v[26:29]
	v_mfma_f32_16x16x32_bf16 v[14:17], v[134:137], v[174:177], v[14:17]
	v_mfma_f32_16x16x32_bf16 v[10:13], v[142:145], v[174:177], v[10:13]
	s_setprio 0
	s_barrier
	s_add_u32 s22, s26, 0x160000
	s_addc_u32 s23, s27, 0
	s_add_i32 s48, s49, s5
	v_lshl_add_u64 v[130:131], s[22:23], 0, v[196:197]
	s_mov_b32 m0, s48
	s_nop 0
	global_load_lds_dwordx4 v[130:131], off
	v_lshl_add_u64 v[130:131], s[22:23], 0, v[194:195]
	s_add_i32 m0, s48, 0x2000
	s_nop 0
	global_load_lds_dwordx4 v[130:131], off
	s_waitcnt vmcnt(6)
	s_barrier
	s_setprio 1
	v_mfma_f32_16x16x32_bf16 v[54:57], v[178:181], v[146:149], v[54:57]
	v_mfma_f32_16x16x32_bf16 v[50:53], v[202:205], v[146:149], v[50:53]
	v_mfma_f32_16x16x32_bf16 v[38:41], v[178:181], v[154:157], v[38:41]
	v_mfma_f32_16x16x32_bf16 v[34:37], v[202:205], v[154:157], v[34:37]
	v_mfma_f32_16x16x32_bf16 v[22:25], v[178:181], v[162:165], v[22:25]
	v_mfma_f32_16x16x32_bf16 v[18:21], v[202:205], v[162:165], v[18:21]
	v_mfma_f32_16x16x32_bf16 v[6:9], v[178:181], v[170:173], v[6:9]
	v_mfma_f32_16x16x32_bf16 v[2:5], v[202:205], v[170:173], v[2:5]
	v_mfma_f32_16x16x32_bf16 v[54:57], v[182:185], v[150:153], v[54:57]
	v_mfma_f32_16x16x32_bf16 v[50:53], v[206:209], v[150:153], v[50:53]
	v_mfma_f32_16x16x32_bf16 v[38:41], v[182:185], v[158:161], v[38:41]
	v_mfma_f32_16x16x32_bf16 v[34:37], v[206:209], v[158:161], v[34:37]
	v_mfma_f32_16x16x32_bf16 v[22:25], v[182:185], v[166:169], v[22:25]
	v_mfma_f32_16x16x32_bf16 v[18:21], v[206:209], v[166:169], v[18:21]
	v_mfma_f32_16x16x32_bf16 v[6:9], v[182:185], v[174:177], v[6:9]
	v_mfma_f32_16x16x32_bf16 v[2:5], v[206:209], v[174:177], v[2:5]
	s_setprio 0
	s_add_i32 s48, 0, 0x18000
	v_add_u32_e32 v142, s48, v191
	s_barrier
	ds_read_b128 v[130:133], v142
	ds_read_b128 v[134:137], v142 offset:1024
	ds_read_b128 v[138:141], v142 offset:2048
	ds_read_b128 v[142:145], v142 offset:3072
	s_add_u32 s22, s28, 0x160000
	s_addc_u32 s23, s29, 0
	s_mov_b32 m0, s36
	v_lshl_add_u64 v[178:179], s[22:23], 0, v[196:197]
	ds_read_b128 v[146:149], v236 offset:32768
	ds_read_b128 v[150:153], v236 offset:33792
	ds_read_b128 v[154:157], v236 offset:34816
	ds_read_b128 v[158:161], v236 offset:35840
	ds_read_b128 v[162:165], v236 offset:36864
	ds_read_b128 v[166:169], v236 offset:37888
	ds_read_b128 v[170:173], v236 offset:38912
	ds_read_b128 v[174:177], v236 offset:39936
	global_load_lds_dwordx4 v[178:179], off
	v_lshl_add_u64 v[178:179], s[22:23], 0, v[194:195]
	s_mov_b32 m0, s37
	s_nop 0
	global_load_lds_dwordx4 v[178:179], off
	s_waitcnt lgkmcnt(8)
	s_barrier
	s_waitcnt lgkmcnt(3)
	s_setprio 1
	v_mfma_f32_16x16x32_bf16 v[126:129], v[130:133], v[146:149], v[126:129]
	v_mfma_f32_16x16x32_bf16 v[122:125], v[138:141], v[146:149], v[122:125]
	v_mfma_f32_16x16x32_bf16 v[110:113], v[130:133], v[154:157], v[110:113]
	v_mfma_f32_16x16x32_bf16 v[106:109], v[138:141], v[154:157], v[106:109]
	v_mfma_f32_16x16x32_bf16 v[94:97], v[130:133], v[162:165], v[94:97]
	v_mfma_f32_16x16x32_bf16 v[90:93], v[138:141], v[162:165], v[90:93]
	s_waitcnt lgkmcnt(0)
	v_mfma_f32_16x16x32_bf16 v[78:81], v[130:133], v[170:173], v[78:81]
	v_mfma_f32_16x16x32_bf16 v[74:77], v[138:141], v[170:173], v[74:77]
	v_mfma_f32_16x16x32_bf16 v[126:129], v[134:137], v[150:153], v[126:129]
	v_mfma_f32_16x16x32_bf16 v[122:125], v[142:145], v[150:153], v[122:125]
	v_mfma_f32_16x16x32_bf16 v[110:113], v[134:137], v[158:161], v[110:113]
	v_mfma_f32_16x16x32_bf16 v[106:109], v[142:145], v[158:161], v[106:109]
	v_mfma_f32_16x16x32_bf16 v[94:97], v[134:137], v[166:169], v[94:97]
	v_mfma_f32_16x16x32_bf16 v[90:93], v[142:145], v[166:169], v[90:93]
	v_mfma_f32_16x16x32_bf16 v[78:81], v[134:137], v[174:177], v[78:81]
	v_mfma_f32_16x16x32_bf16 v[74:77], v[142:145], v[174:177], v[74:77]
	s_setprio 0
	s_barrier
	s_add_i32 s28, 0, 0x1c000
	s_add_i32 s22, s48, s5
	v_add_u32_e32 v206, s28, v191
	v_lshl_add_u64 v[210:211], v[210:211], 0, s[6:7]
	s_mov_b32 m0, s22
	ds_read_b128 v[178:181], v206
	ds_read_b128 v[182:185], v206 offset:1024
	ds_read_b128 v[202:205], v206 offset:2048
	ds_read_b128 v[206:209], v206 offset:3072
	global_load_lds_dwordx4 v[210:211], off
	v_lshl_add_u64 v[210:211], v[212:213], 0, s[6:7]
	s_add_i32 m0, s22, 0x2000
	s_nop 0
	global_load_lds_dwordx4 v[210:211], off
	s_barrier
	s_waitcnt lgkmcnt(1)
	s_setprio 1
	v_mfma_f32_16x16x32_bf16 v[118:121], v[178:181], v[146:149], v[118:121]
	v_mfma_f32_16x16x32_bf16 v[114:117], v[202:205], v[146:149], v[114:117]
	v_mfma_f32_16x16x32_bf16 v[102:105], v[178:181], v[154:157], v[102:105]
	v_mfma_f32_16x16x32_bf16 v[98:101], v[202:205], v[154:157], v[98:101]
	v_mfma_f32_16x16x32_bf16 v[86:89], v[178:181], v[162:165], v[86:89]
	v_mfma_f32_16x16x32_bf16 v[82:85], v[202:205], v[162:165], v[82:85]
	s_waitcnt lgkmcnt(0)
	v_mfma_f32_16x16x32_bf16 v[70:73], v[178:181], v[170:173], v[70:73]
	v_mfma_f32_16x16x32_bf16 v[66:69], v[202:205], v[170:173], v[66:69]
	v_mfma_f32_16x16x32_bf16 v[118:121], v[182:185], v[150:153], v[118:121]
	v_mfma_f32_16x16x32_bf16 v[114:117], v[206:209], v[150:153], v[114:117]
	v_mfma_f32_16x16x32_bf16 v[102:105], v[182:185], v[158:161], v[102:105]
	v_mfma_f32_16x16x32_bf16 v[98:101], v[206:209], v[158:161], v[98:101]
	v_mfma_f32_16x16x32_bf16 v[86:89], v[182:185], v[166:169], v[86:89]
	v_mfma_f32_16x16x32_bf16 v[82:85], v[206:209], v[166:169], v[82:85]
	v_mfma_f32_16x16x32_bf16 v[70:73], v[182:185], v[174:177], v[70:73]
	v_mfma_f32_16x16x32_bf16 v[66:69], v[206:209], v[174:177], v[66:69]
	s_setprio 0
	s_mov_b32 m0, s38
	v_lshl_add_u64 v[210:211], v[220:221], 0, s[6:7]
	s_barrier
	ds_read_b128 v[146:149], v236 offset:49152
	ds_read_b128 v[150:153], v236 offset:50176
	ds_read_b128 v[154:157], v236 offset:51200
	ds_read_b128 v[158:161], v236 offset:52224
	ds_read_b128 v[162:165], v236 offset:53248
	ds_read_b128 v[166:169], v236 offset:54272
	ds_read_b128 v[170:173], v236 offset:55296
	ds_read_b128 v[174:177], v236 offset:56320
	global_load_lds_dwordx4 v[210:211], off
	v_lshl_add_u64 v[210:211], v[222:223], 0, s[6:7]
	s_mov_b32 m0, s39
	s_nop 0
	global_load_lds_dwordx4 v[210:211], off
	s_barrier
	s_waitcnt lgkmcnt(3)
	s_setprio 1
	v_mfma_f32_16x16x32_bf16 v[62:65], v[130:133], v[146:149], v[62:65]
	v_mfma_f32_16x16x32_bf16 v[58:61], v[138:141], v[146:149], v[58:61]
	v_mfma_f32_16x16x32_bf16 v[46:49], v[130:133], v[154:157], v[46:49]
	v_mfma_f32_16x16x32_bf16 v[42:45], v[138:141], v[154:157], v[42:45]
	v_mfma_f32_16x16x32_bf16 v[30:33], v[130:133], v[162:165], v[30:33]
	v_mfma_f32_16x16x32_bf16 v[26:29], v[138:141], v[162:165], v[26:29]
	s_waitcnt lgkmcnt(0)
	v_mfma_f32_16x16x32_bf16 v[14:17], v[130:133], v[170:173], v[14:17]
	v_mfma_f32_16x16x32_bf16 v[10:13], v[138:141], v[170:173], v[10:13]
	v_mfma_f32_16x16x32_bf16 v[62:65], v[134:137], v[150:153], v[62:65]
	v_mfma_f32_16x16x32_bf16 v[58:61], v[142:145], v[150:153], v[58:61]
	v_mfma_f32_16x16x32_bf16 v[46:49], v[134:137], v[158:161], v[46:49]
	v_mfma_f32_16x16x32_bf16 v[42:45], v[142:145], v[158:161], v[42:45]
	v_mfma_f32_16x16x32_bf16 v[30:33], v[134:137], v[166:169], v[30:33]
	v_mfma_f32_16x16x32_bf16 v[26:29], v[142:145], v[166:169], v[26:29]
	v_mfma_f32_16x16x32_bf16 v[14:17], v[134:137], v[174:177], v[14:17]
	v_mfma_f32_16x16x32_bf16 v[10:13], v[142:145], v[174:177], v[10:13]
	s_setprio 0
	s_barrier
	s_add_u32 s22, s26, 0x160080
	s_addc_u32 s23, s27, 0
	s_add_i32 s26, s28, s5
	v_lshl_add_u64 v[130:131], s[22:23], 0, v[196:197]
	s_mov_b32 m0, s26
	s_nop 0
	global_load_lds_dwordx4 v[130:131], off
	v_lshl_add_u64 v[130:131], s[22:23], 0, v[194:195]
	s_add_i32 m0, s26, 0x2000
	s_nop 0
	global_load_lds_dwordx4 v[130:131], off
	s_waitcnt vmcnt(6)
	s_barrier
	s_setprio 1
	v_mfma_f32_16x16x32_bf16 v[54:57], v[178:181], v[146:149], v[54:57]
	v_mfma_f32_16x16x32_bf16 v[50:53], v[202:205], v[146:149], v[50:53]
	v_mfma_f32_16x16x32_bf16 v[38:41], v[178:181], v[154:157], v[38:41]
	v_mfma_f32_16x16x32_bf16 v[34:37], v[202:205], v[154:157], v[34:37]
	v_mfma_f32_16x16x32_bf16 v[22:25], v[178:181], v[162:165], v[22:25]
	v_mfma_f32_16x16x32_bf16 v[18:21], v[202:205], v[162:165], v[18:21]
	v_mfma_f32_16x16x32_bf16 v[6:9], v[178:181], v[170:173], v[6:9]
	v_mfma_f32_16x16x32_bf16 v[2:5], v[202:205], v[170:173], v[2:5]
	v_mfma_f32_16x16x32_bf16 v[54:57], v[182:185], v[150:153], v[54:57]
	v_mfma_f32_16x16x32_bf16 v[50:53], v[206:209], v[150:153], v[50:53]
	v_mfma_f32_16x16x32_bf16 v[38:41], v[182:185], v[158:161], v[38:41]
	v_mfma_f32_16x16x32_bf16 v[34:37], v[206:209], v[158:161], v[34:37]
	v_mfma_f32_16x16x32_bf16 v[22:25], v[182:185], v[166:169], v[22:25]
	v_mfma_f32_16x16x32_bf16 v[18:21], v[206:209], v[166:169], v[18:21]
	v_mfma_f32_16x16x32_bf16 v[6:9], v[182:185], v[174:177], v[6:9]
	v_mfma_f32_16x16x32_bf16 v[2:5], v[206:209], v[174:177], v[2:5]
	s_setprio 0
	s_add_i32 s47, s47, 2
	s_add_u32 s45, s45, 0x100
	s_addc_u32 s46, s46, 0
	s_cmpk_gt_u32 s47, 0x55
	s_mov_b64 s[22:23], s[24:25]
	s_barrier
	s_cbranch_scc0 .LBB0_695
	v_lshl_add_u32 v202, s43, 8, v1
	v_lshl_or_b32 v204, s44, 8, v192
	v_ashrrev_i32_e32 v205, 31, v204
	v_ashrrev_i32_e32 v203, 31, v202
	v_lshl_add_u64 v[206:207], v[204:205], 2, s[18:19]
	v_lshlrev_b64 v[130:131], 13, v[202:203]
	v_lshl_add_u64 v[130:131], v[206:207], 0, v[130:131]
	global_load_dwordx4 v[238:241], v[130:131], off
	global_load_dwordx4 v[242:245], v[130:131], off offset:64
	global_load_dwordx4 v[182:185], v[130:131], off offset:512
	global_load_dwordx4 v[178:181], v[130:131], off offset:576
	v_or_b32_e32 v212, 16, v202
	v_ashrrev_i32_e32 v213, 31, v212
	v_lshlrev_b64 v[130:131], 13, v[212:213]
	v_or_b32_e32 v210, 32, v202
	v_lshl_add_u64 v[130:131], v[206:207], 0, v[130:131]
	v_ashrrev_i32_e32 v211, 31, v210
	global_load_dwordx4 v[174:177], v[130:131], off
	global_load_dwordx4 v[170:173], v[130:131], off offset:64
	global_load_dwordx4 v[166:169], v[130:131], off offset:512
	global_load_dwordx4 v[162:165], v[130:131], off offset:576
	v_lshlrev_b64 v[130:131], 13, v[210:211]
	v_or_b32_e32 v208, 48, v202
	v_lshl_add_u64 v[130:131], v[206:207], 0, v[130:131]
	v_ashrrev_i32_e32 v209, 31, v208
	global_load_dwordx4 v[158:161], v[130:131], off
	global_load_dwordx4 v[150:153], v[130:131], off offset:64
	global_load_dwordx4 v[146:149], v[130:131], off offset:512
	global_load_dwordx4 v[138:141], v[130:131], off offset:576
	v_lshlrev_b64 v[130:131], 13, v[208:209]
	v_lshl_add_u64 v[130:131], v[206:207], 0, v[130:131]
	global_load_dwordx4 v[154:157], v[130:131], off
	global_load_dwordx4 v[142:145], v[130:131], off offset:64
	global_load_dwordx4 v[134:137], v[130:131], off offset:512
	s_nop 0
	global_load_dwordx4 v[130:133], v[130:131], off offset:576
	v_lshlrev_b64 v[220:221], 11, v[202:203]
	v_readlane_b32 s24, v254, 46
	v_readlane_b32 s22, v254, 1
	v_lshl_add_u64 v[220:221], v[220:221], 0, v[204:205]
	v_readlane_b32 s25, v254, 47
	v_readlane_b32 s23, v254, 2
	v_readlane_b32 s26, v254, 48
	v_lshl_add_u64 v[222:223], v[220:221], 2, s[24:25]
	v_lshl_add_u64 v[220:221], v[220:221], 1, s[22:23]
	v_readlane_b32 s27, v254, 49
	s_waitcnt vmcnt(0)
	v_pk_fma_f32 v[128:129], v[128:129], 0.5, v[240:241] op_sel_hi:[1,0,1]
	v_pk_fma_f32 v[126:127], v[126:127], 0.5, v[238:239] op_sel_hi:[1,0,1]
	v_cvt_pk_bf16_f32 v239, v128, v129
	v_cvt_pk_bf16_f32 v238, v126, v127
	v_mul_f32_e32 v224, v127, v127
	v_pk_fma_f32 v[124:125], v[124:125], 0.5, v[244:245] op_sel_hi:[1,0,1]
	v_pk_fma_f32 v[122:123], v[122:123], 0.5, v[242:243] op_sel_hi:[1,0,1]
	global_store_dwordx4 v[222:223], v[126:129], off
	global_store_dwordx2 v[220:221], v[238:239], off
	v_fmac_f32_e32 v224, v126, v126
	global_store_dwordx4 v[222:223], v[122:125], off offset:64
	v_cvt_pk_bf16_f32 v126, v122, v123
	v_fmac_f32_e32 v224, v128, v128
	v_mul_f32_e32 v123, v123, v123
	v_fmac_f32_e32 v123, v122, v122
	v_fmac_f32_e32 v123, v124, v124
	v_fmac_f32_e32 v224, v129, v129
	v_cvt_pk_bf16_f32 v127, v124, v125
	v_fmac_f32_e32 v123, v125, v125
	v_pk_fma_f32 v[120:121], v[120:121], 0.5, v[184:185] op_sel_hi:[1,0,1]
	v_pk_fma_f32 v[118:119], v[118:119], 0.5, v[182:183] op_sel_hi:[1,0,1]
	global_store_dwordx2 v[220:221], v[126:127], off offset:32
	v_add_f32_e32 v124, v224, v123
	global_store_dwordx4 v[222:223], v[118:121], off offset:512
	v_cvt_pk_bf16_f32 v122, v118, v119
	v_cvt_pk_bf16_f32 v123, v120, v121
	v_mul_f32_e32 v119, v119, v119
	v_pk_fma_f32 v[116:117], v[116:117], 0.5, v[180:181] op_sel_hi:[1,0,1]
	v_pk_fma_f32 v[114:115], v[114:115], 0.5, v[178:179] op_sel_hi:[1,0,1]
	global_store_dwordx2 v[220:221], v[122:123], off offset:256
	v_fmac_f32_e32 v119, v118, v118
	global_store_dwordx4 v[222:223], v[114:117], off offset:576
	v_cvt_pk_bf16_f32 v118, v114, v115
	v_fmac_f32_e32 v119, v120, v120
	v_mul_f32_e32 v115, v115, v115
	v_fmac_f32_e32 v115, v114, v114
	v_fmac_f32_e32 v119, v121, v121
	v_fmac_f32_e32 v115, v116, v116
	v_add_f32_e32 v120, v124, v119
	v_fmac_f32_e32 v115, v117, v117
	v_add_f32_e32 v114, v120, v115
	v_mov_b32_e32 v115, v114
	s_nop 1
	v_permlane32_swap_b32_e32 v114, v115
	v_add_f32_e32 v114, v114, v115
	v_mov_b32_e32 v115, v114
	v_cvt_pk_bf16_f32 v119, v116, v117
	s_nop 0
	v_permlane16_swap_b32_e32 v114, v115
	global_store_dwordx2 v[220:221], v[118:119], off offset:288
	s_and_saveexec_b64 s[22:23], s[10:11]
	s_cbranch_execz .LBB0_698
	v_lshl_add_u64 v[116:117], v[202:203], 2, s[20:21]
	v_add_f32_e32 v114, v114, v115
	global_atomic_add_f32 v[116:117], v114, off

.LBB0_732:
	s_add_u32 s18, s16, 0x100
	s_addc_u32 s19, s17, 0
	s_add_i32 s40, 0, 0x10000
	v_add_u32_e32 v153, s40, v150
	ds_read_b128 v[138:141], v153
	ds_read_b128 v[142:145], v153 offset:1024
	ds_read_b128 v[146:149], v153 offset:2048
	ds_read_b128 v[154:157], v153 offset:3072
	s_cmpk_eq_i32 s39, 0x54
	s_cselect_b32 s23, s13, s19
	s_cselect_b32 s22, s12, s18
	s_cselect_b32 s21, s15, s38
	s_cselect_b32 s20, s14, s37
	v_lshl_add_u64 v[198:199], s[16:17], 0, v[134:135]
	s_add_i32 m0, s24, 0xc000
	ds_read_b128 v[158:161], v152
	ds_read_b128 v[162:165], v152 offset:1024
	ds_read_b128 v[166:169], v152 offset:2048
	ds_read_b128 v[170:173], v152 offset:3072
	ds_read_b128 v[174:177], v152 offset:4096
	ds_read_b128 v[178:181], v152 offset:5120
	ds_read_b128 v[182:185], v152 offset:6144
	ds_read_b128 v[194:197], v152 offset:7168
	global_load_lds_dwordx4 v[198:199], off
	v_lshl_add_u64 v[198:199], s[16:17], 0, v[136:137]
	s_add_i32 m0, s24, 0xe000
	s_nop 0
	global_load_lds_dwordx4 v[198:199], off
	s_waitcnt lgkmcnt(8)
	s_barrier
	s_waitcnt lgkmcnt(3)
	s_setprio 1
	v_mfma_f32_16x16x32_bf16 v[126:129], v[138:141], v[158:161], v[126:129]
	v_mfma_f32_16x16x32_bf16 v[122:125], v[146:149], v[158:161], v[122:125]
	v_mfma_f32_16x16x32_bf16 v[118:121], v[138:141], v[166:169], v[118:121]
	v_mfma_f32_16x16x32_bf16 v[114:117], v[146:149], v[166:169], v[114:117]
	v_mfma_f32_16x16x32_bf16 v[106:109], v[138:141], v[174:177], v[106:109]
	v_mfma_f32_16x16x32_bf16 v[98:101], v[146:149], v[174:177], v[98:101]
	s_waitcnt lgkmcnt(0)
	v_mfma_f32_16x16x32_bf16 v[90:93], v[138:141], v[182:185], v[90:93]
	v_mfma_f32_16x16x32_bf16 v[82:85], v[146:149], v[182:185], v[82:85]
	v_mfma_f32_16x16x32_bf16 v[126:129], v[142:145], v[162:165], v[126:129]
	v_mfma_f32_16x16x32_bf16 v[122:125], v[154:157], v[162:165], v[122:125]
	v_mfma_f32_16x16x32_bf16 v[118:121], v[142:145], v[170:173], v[118:121]
	v_mfma_f32_16x16x32_bf16 v[114:117], v[154:157], v[170:173], v[114:117]
	v_mfma_f32_16x16x32_bf16 v[106:109], v[142:145], v[178:181], v[106:109]
	v_mfma_f32_16x16x32_bf16 v[98:101], v[154:157], v[178:181], v[98:101]
	v_mfma_f32_16x16x32_bf16 v[90:93], v[142:145], v[194:197], v[90:93]
	v_mfma_f32_16x16x32_bf16 v[82:85], v[154:157], v[194:197], v[82:85]
	s_setprio 0
	s_barrier
	s_add_i32 s41, 0, 0x14000
	s_add_i32 s16, s40, s5
	v_add_u32_e32 v153, s41, v150
	v_lshl_add_u64 v[220:221], s[20:21], 0, v[132:133]
	s_mov_b32 m0, s16
	ds_read_b128 v[198:201], v153
	ds_read_b128 v[202:205], v153 offset:1024
	ds_read_b128 v[206:209], v153 offset:2048
	ds_read_b128 v[210:213], v153 offset:3072
	global_load_lds_dwordx4 v[220:221], off
	v_lshl_add_u64 v[222:223], s[20:21], 0, v[130:131]
	s_add_i32 m0, s16, 0x2000
	s_nop 0
	global_load_lds_dwordx4 v[222:223], off
	s_barrier
	s_waitcnt lgkmcnt(1)
	s_setprio 1
	v_mfma_f32_16x16x32_bf16 v[110:113], v[198:201], v[158:161], v[110:113]
	v_mfma_f32_16x16x32_bf16 v[102:105], v[206:209], v[158:161], v[102:105]
	v_mfma_f32_16x16x32_bf16 v[94:97], v[198:201], v[166:169], v[94:97]
	v_mfma_f32_16x16x32_bf16 v[86:89], v[206:209], v[166:169], v[86:89]
	v_mfma_f32_16x16x32_bf16 v[78:81], v[198:201], v[174:177], v[78:81]
	v_mfma_f32_16x16x32_bf16 v[74:77], v[206:209], v[174:177], v[74:77]
	s_waitcnt lgkmcnt(0)
	v_mfma_f32_16x16x32_bf16 v[70:73], v[198:201], v[182:185], v[70:73]
	v_mfma_f32_16x16x32_bf16 v[66:69], v[206:209], v[182:185], v[66:69]
	v_mfma_f32_16x16x32_bf16 v[110:113], v[202:205], v[162:165], v[110:113]
	v_mfma_f32_16x16x32_bf16 v[102:105], v[210:213], v[162:165], v[102:105]
	v_mfma_f32_16x16x32_bf16 v[94:97], v[202:205], v[170:173], v[94:97]
	v_mfma_f32_16x16x32_bf16 v[86:89], v[210:213], v[170:173], v[86:89]
	v_mfma_f32_16x16x32_bf16 v[78:81], v[202:205], v[178:181], v[78:81]
	v_mfma_f32_16x16x32_bf16 v[74:77], v[210:213], v[178:181], v[74:77]
	v_mfma_f32_16x16x32_bf16 v[70:73], v[202:205], v[194:197], v[70:73]
	v_mfma_f32_16x16x32_bf16 v[66:69], v[210:213], v[194:197], v[66:69]
	s_setprio 0
	s_mov_b32 m0, s24
	v_lshl_add_u64 v[236:237], s[22:23], 0, v[132:133]
	s_barrier
	ds_read_b128 v[158:161], v152 offset:16384
	ds_read_b128 v[162:165], v152 offset:17408
	ds_read_b128 v[166:169], v152 offset:18432
	ds_read_b128 v[170:173], v152 offset:19456
	ds_read_b128 v[174:177], v152 offset:20480
	ds_read_b128 v[178:181], v152 offset:21504
	ds_read_b128 v[182:185], v152 offset:22528
	ds_read_b128 v[194:197], v152 offset:23552
	global_load_lds_dwordx4 v[236:237], off
	v_lshl_add_u64 v[238:239], s[22:23], 0, v[130:131]
	s_mov_b32 m0, s25
	s_nop 0
	global_load_lds_dwordx4 v[238:239], off
	s_barrier
	s_waitcnt lgkmcnt(3)
	s_setprio 1
	v_mfma_f32_16x16x32_bf16 v[62:65], v[138:141], v[158:161], v[62:65]
	v_mfma_f32_16x16x32_bf16 v[58:61], v[146:149], v[158:161], v[58:61]
	v_mfma_f32_16x16x32_bf16 v[54:57], v[138:141], v[166:169], v[54:57]
	v_mfma_f32_16x16x32_bf16 v[46:49], v[146:149], v[166:169], v[46:49]
	v_mfma_f32_16x16x32_bf16 v[38:41], v[138:141], v[174:177], v[38:41]
	v_mfma_f32_16x16x32_bf16 v[30:33], v[146:149], v[174:177], v[30:33]
	s_waitcnt lgkmcnt(0)
	v_mfma_f32_16x16x32_bf16 v[22:25], v[138:141], v[182:185], v[22:25]
	v_mfma_f32_16x16x32_bf16 v[10:13], v[146:149], v[182:185], v[10:13]
	v_mfma_f32_16x16x32_bf16 v[62:65], v[142:145], v[162:165], v[62:65]
	v_mfma_f32_16x16x32_bf16 v[58:61], v[154:157], v[162:165], v[58:61]
	v_mfma_f32_16x16x32_bf16 v[54:57], v[142:145], v[170:173], v[54:57]
	v_mfma_f32_16x16x32_bf16 v[46:49], v[154:157], v[170:173], v[46:49]
	v_mfma_f32_16x16x32_bf16 v[38:41], v[142:145], v[178:181], v[38:41]
	v_mfma_f32_16x16x32_bf16 v[30:33], v[154:157], v[178:181], v[30:33]
	v_mfma_f32_16x16x32_bf16 v[22:25], v[142:145], v[194:197], v[22:25]
	v_mfma_f32_16x16x32_bf16 v[10:13], v[154:157], v[194:197], v[10:13]
	s_setprio 0
	s_barrier
	s_add_u32 s16, s20, 0x160000
	s_addc_u32 s17, s21, 0
	s_add_i32 s40, s41, s5
	v_lshl_add_u64 v[138:139], s[16:17], 0, v[132:133]
	s_mov_b32 m0, s40
	s_nop 0
	global_load_lds_dwordx4 v[138:139], off
	v_lshl_add_u64 v[138:139], s[16:17], 0, v[130:131]
	s_add_i32 m0, s40, 0x2000
	s_nop 0
	global_load_lds_dwordx4 v[138:139], off
	s_waitcnt vmcnt(6)
	s_barrier
	s_setprio 1
	v_mfma_f32_16x16x32_bf16 v[50:53], v[198:201], v[158:161], v[50:53]
	v_mfma_f32_16x16x32_bf16 v[42:45], v[206:209], v[158:161], v[42:45]
	v_mfma_f32_16x16x32_bf16 v[34:37], v[198:201], v[166:169], v[34:37]
	v_mfma_f32_16x16x32_bf16 v[26:29], v[206:209], v[166:169], v[26:29]
	v_mfma_f32_16x16x32_bf16 v[18:21], v[198:201], v[174:177], v[18:21]
	v_mfma_f32_16x16x32_bf16 v[14:17], v[206:209], v[174:177], v[14:17]
	v_mfma_f32_16x16x32_bf16 v[6:9], v[198:201], v[182:185], v[6:9]
	v_mfma_f32_16x16x32_bf16 v[2:5], v[206:209], v[182:185], v[2:5]
	v_mfma_f32_16x16x32_bf16 v[50:53], v[202:205], v[162:165], v[50:53]
	v_mfma_f32_16x16x32_bf16 v[42:45], v[210:213], v[162:165], v[42:45]
	v_mfma_f32_16x16x32_bf16 v[34:37], v[202:205], v[170:173], v[34:37]
	v_mfma_f32_16x16x32_bf16 v[26:29], v[210:213], v[170:173], v[26:29]
	v_mfma_f32_16x16x32_bf16 v[18:21], v[202:205], v[178:181], v[18:21]
	v_mfma_f32_16x16x32_bf16 v[14:17], v[210:213], v[178:181], v[14:17]
	v_mfma_f32_16x16x32_bf16 v[6:9], v[202:205], v[194:197], v[6:9]
	v_mfma_f32_16x16x32_bf16 v[2:5], v[210:213], v[194:197], v[2:5]
	s_setprio 0
	s_add_i32 s40, 0, 0x18000
	v_add_u32_e32 v153, s40, v150
	s_barrier
	ds_read_b128 v[138:141], v153
	ds_read_b128 v[142:145], v153 offset:1024
	ds_read_b128 v[146:149], v153 offset:2048
	ds_read_b128 v[154:157], v153 offset:3072
	s_add_u32 s16, s22, 0x160000
	s_addc_u32 s17, s23, 0
	s_mov_b32 m0, s26
	v_lshl_add_u64 v[198:199], s[16:17], 0, v[132:133]
	ds_read_b128 v[158:161], v152 offset:32768
	ds_read_b128 v[162:165], v152 offset:33792
	ds_read_b128 v[166:169], v152 offset:34816
	ds_read_b128 v[170:173], v152 offset:35840
	ds_read_b128 v[174:177], v152 offset:36864
	ds_read_b128 v[178:181], v152 offset:37888
	ds_read_b128 v[182:185], v152 offset:38912
	ds_read_b128 v[194:197], v152 offset:39936
	global_load_lds_dwordx4 v[198:199], off
	v_lshl_add_u64 v[198:199], s[16:17], 0, v[130:131]
	s_mov_b32 m0, s27
	s_nop 0
	global_load_lds_dwordx4 v[198:199], off
	s_waitcnt lgkmcnt(8)
	s_barrier
	s_waitcnt lgkmcnt(3)
	s_setprio 1
	v_mfma_f32_16x16x32_bf16 v[126:129], v[138:141], v[158:161], v[126:129]
	v_mfma_f32_16x16x32_bf16 v[122:125], v[146:149], v[158:161], v[122:125]
	v_mfma_f32_16x16x32_bf16 v[118:121], v[138:141], v[166:169], v[118:121]
	v_mfma_f32_16x16x32_bf16 v[114:117], v[146:149], v[166:169], v[114:117]
	v_mfma_f32_16x16x32_bf16 v[106:109], v[138:141], v[174:177], v[106:109]
	v_mfma_f32_16x16x32_bf16 v[98:101], v[146:149], v[174:177], v[98:101]
	s_waitcnt lgkmcnt(0)
	v_mfma_f32_16x16x32_bf16 v[90:93], v[138:141], v[182:185], v[90:93]
	v_mfma_f32_16x16x32_bf16 v[82:85], v[146:149], v[182:185], v[82:85]
	v_mfma_f32_16x16x32_bf16 v[126:129], v[142:145], v[162:165], v[126:129]
	v_mfma_f32_16x16x32_bf16 v[122:125], v[154:157], v[162:165], v[122:125]
	v_mfma_f32_16x16x32_bf16 v[118:121], v[142:145], v[170:173], v[118:121]
	v_mfma_f32_16x16x32_bf16 v[114:117], v[154:157], v[170:173], v[114:117]
	v_mfma_f32_16x16x32_bf16 v[106:109], v[142:145], v[178:181], v[106:109]
	v_mfma_f32_16x16x32_bf16 v[98:101], v[154:157], v[178:181], v[98:101]
	v_mfma_f32_16x16x32_bf16 v[90:93], v[142:145], v[194:197], v[90:93]
	v_mfma_f32_16x16x32_bf16 v[82:85], v[154:157], v[194:197], v[82:85]
	s_setprio 0
	s_barrier
	s_add_i32 s22, 0, 0x1c000
	s_add_i32 s16, s40, s5
	v_add_u32_e32 v153, s22, v150
	v_lshl_add_u64 v[220:221], v[220:221], 0, s[6:7]
	s_mov_b32 m0, s16
	ds_read_b128 v[198:201], v153
	ds_read_b128 v[202:205], v153 offset:1024
	ds_read_b128 v[206:209], v153 offset:2048
	ds_read_b128 v[210:213], v153 offset:3072
	global_load_lds_dwordx4 v[220:221], off
	v_lshl_add_u64 v[220:221], v[222:223], 0, s[6:7]
	s_add_i32 m0, s16, 0x2000
	s_nop 0
	global_load_lds_dwordx4 v[220:221], off
	s_barrier
	s_waitcnt lgkmcnt(1)
	s_setprio 1
	v_mfma_f32_16x16x32_bf16 v[110:113], v[198:201], v[158:161], v[110:113]
	v_mfma_f32_16x16x32_bf16 v[102:105], v[206:209], v[158:161], v[102:105]
	v_mfma_f32_16x16x32_bf16 v[94:97], v[198:201], v[166:169], v[94:97]
	v_mfma_f32_16x16x32_bf16 v[86:89], v[206:209], v[166:169], v[86:89]
	v_mfma_f32_16x16x32_bf16 v[78:81], v[198:201], v[174:177], v[78:81]
	v_mfma_f32_16x16x32_bf16 v[74:77], v[206:209], v[174:177], v[74:77]
	s_waitcnt lgkmcnt(0)
	v_mfma_f32_16x16x32_bf16 v[70:73], v[198:201], v[182:185], v[70:73]
	v_mfma_f32_16x16x32_bf16 v[66:69], v[206:209], v[182:185], v[66:69]
	v_mfma_f32_16x16x32_bf16 v[110:113], v[202:205], v[162:165], v[110:113]
	v_mfma_f32_16x16x32_bf16 v[102:105], v[210:213], v[162:165], v[102:105]
	v_mfma_f32_16x16x32_bf16 v[94:97], v[202:205], v[170:173], v[94:97]
	v_mfma_f32_16x16x32_bf16 v[86:89], v[210:213], v[170:173], v[86:89]
	v_mfma_f32_16x16x32_bf16 v[78:81], v[202:205], v[178:181], v[78:81]
	v_mfma_f32_16x16x32_bf16 v[74:77], v[210:213], v[178:181], v[74:77]
	v_mfma_f32_16x16x32_bf16 v[70:73], v[202:205], v[194:197], v[70:73]
	v_mfma_f32_16x16x32_bf16 v[66:69], v[210:213], v[194:197], v[66:69]
	s_setprio 0
	s_mov_b32 m0, s28
	v_lshl_add_u64 v[220:221], v[236:237], 0, s[6:7]
	s_barrier
	ds_read_b128 v[158:161], v152 offset:49152
	ds_read_b128 v[162:165], v152 offset:50176
	ds_read_b128 v[166:169], v152 offset:51200
	ds_read_b128 v[170:173], v152 offset:52224
	ds_read_b128 v[174:177], v152 offset:53248
	ds_read_b128 v[178:181], v152 offset:54272
	ds_read_b128 v[182:185], v152 offset:55296
	ds_read_b128 v[194:197], v152 offset:56320
	global_load_lds_dwordx4 v[220:221], off
	v_lshl_add_u64 v[220:221], v[238:239], 0, s[6:7]
	s_mov_b32 m0, s29
	s_nop 0
	global_load_lds_dwordx4 v[220:221], off
	s_barrier
	s_waitcnt lgkmcnt(3)
	s_setprio 1
	v_mfma_f32_16x16x32_bf16 v[62:65], v[138:141], v[158:161], v[62:65]
	v_mfma_f32_16x16x32_bf16 v[58:61], v[146:149], v[158:161], v[58:61]
	v_mfma_f32_16x16x32_bf16 v[54:57], v[138:141], v[166:169], v[54:57]
	v_mfma_f32_16x16x32_bf16 v[46:49], v[146:149], v[166:169], v[46:49]
	v_mfma_f32_16x16x32_bf16 v[38:41], v[138:141], v[174:177], v[38:41]
	v_mfma_f32_16x16x32_bf16 v[30:33], v[146:149], v[174:177], v[30:33]
	s_waitcnt lgkmcnt(0)
	v_mfma_f32_16x16x32_bf16 v[22:25], v[138:141], v[182:185], v[22:25]
	v_mfma_f32_16x16x32_bf16 v[10:13], v[146:149], v[182:185], v[10:13]
	v_mfma_f32_16x16x32_bf16 v[62:65], v[142:145], v[162:165], v[62:65]
	v_mfma_f32_16x16x32_bf16 v[58:61], v[154:157], v[162:165], v[58:61]
	v_mfma_f32_16x16x32_bf16 v[54:57], v[142:145], v[170:173], v[54:57]
	v_mfma_f32_16x16x32_bf16 v[46:49], v[154:157], v[170:173], v[46:49]
	v_mfma_f32_16x16x32_bf16 v[38:41], v[142:145], v[178:181], v[38:41]
	v_mfma_f32_16x16x32_bf16 v[30:33], v[154:157], v[178:181], v[30:33]
	v_mfma_f32_16x16x32_bf16 v[22:25], v[142:145], v[194:197], v[22:25]
	v_mfma_f32_16x16x32_bf16 v[10:13], v[154:157], v[194:197], v[10:13]
	s_setprio 0
	s_barrier
	s_add_u32 s16, s20, 0x160080
	s_addc_u32 s17, s21, 0
	s_add_i32 s20, s22, s5
	v_lshl_add_u64 v[138:139], s[16:17], 0, v[132:133]
	s_mov_b32 m0, s20
	s_nop 0
	global_load_lds_dwordx4 v[138:139], off
	v_lshl_add_u64 v[138:139], s[16:17], 0, v[130:131]
	s_add_i32 m0, s20, 0x2000
	s_nop 0
	global_load_lds_dwordx4 v[138:139], off
	s_waitcnt vmcnt(6)
	s_barrier
	s_setprio 1
	v_mfma_f32_16x16x32_bf16 v[50:53], v[198:201], v[158:161], v[50:53]
	v_mfma_f32_16x16x32_bf16 v[42:45], v[206:209], v[158:161], v[42:45]
	v_mfma_f32_16x16x32_bf16 v[34:37], v[198:201], v[166:169], v[34:37]
	v_mfma_f32_16x16x32_bf16 v[26:29], v[206:209], v[166:169], v[26:29]
	v_mfma_f32_16x16x32_bf16 v[18:21], v[198:201], v[174:177], v[18:21]
	v_mfma_f32_16x16x32_bf16 v[14:17], v[206:209], v[174:177], v[14:17]
	v_mfma_f32_16x16x32_bf16 v[6:9], v[198:201], v[182:185], v[6:9]
	v_mfma_f32_16x16x32_bf16 v[2:5], v[206:209], v[182:185], v[2:5]
	v_mfma_f32_16x16x32_bf16 v[50:53], v[202:205], v[162:165], v[50:53]
	v_mfma_f32_16x16x32_bf16 v[42:45], v[210:213], v[162:165], v[42:45]
	v_mfma_f32_16x16x32_bf16 v[34:37], v[202:205], v[170:173], v[34:37]
	v_mfma_f32_16x16x32_bf16 v[26:29], v[210:213], v[170:173], v[26:29]
	v_mfma_f32_16x16x32_bf16 v[18:21], v[202:205], v[178:181], v[18:21]
	v_mfma_f32_16x16x32_bf16 v[14:17], v[210:213], v[178:181], v[14:17]
	v_mfma_f32_16x16x32_bf16 v[6:9], v[202:205], v[194:197], v[6:9]
	v_mfma_f32_16x16x32_bf16 v[2:5], v[210:213], v[194:197], v[2:5]
	s_setprio 0
	s_add_i32 s39, s39, 2
	s_add_u32 s37, s37, 0x100
	s_addc_u32 s38, s38, 0
	s_cmpk_gt_u32 s39, 0x55
	s_mov_b64 s[16:17], s[18:19]
	s_barrier
	s_cbranch_scc0 .LBB0_732
	v_lshl_or_b32 v138, s36, 8, v151
	v_lshl_add_u32 v140, s35, 8, v1
	v_ashrrev_i32_e32 v139, 31, v138
	v_readlane_b32 s20, v254, 46
	v_lshlrev_b64 v[138:139], 2, v[138:139]
	v_readlane_b32 s21, v254, 47
	v_ashrrev_i32_e32 v141, 31, v140
	v_lshlrev_b64 v[144:145], 13, v[140:141]
	v_lshl_add_u64 v[142:143], s[20:21], 0, v[138:139]
	v_or_b32_e32 v166, 16, v140
	v_lshl_add_u64 v[162:163], v[142:143], 0, v[144:145]
	v_ashrrev_i32_e32 v167, 31, v166
	global_load_dwordx4 v[146:149], v[162:163], off
	global_load_dwordx4 v[154:157], v[162:163], off offset:64
	global_load_dwordx4 v[158:161], v[162:163], off offset:512
	s_nop 0
	global_load_dwordx4 v[162:165], v[162:163], off offset:576
	v_lshlrev_b64 v[220:221], 13, v[166:167]
	v_or_b32_e32 v182, 32, v140
	v_lshl_add_u64 v[178:179], v[142:143], 0, v[220:221]
	v_ashrrev_i32_e32 v183, 31, v182
	global_load_dwordx4 v[166:169], v[178:179], off
	global_load_dwordx4 v[170:173], v[178:179], off offset:64
	global_load_dwordx4 v[174:177], v[178:179], off offset:512
	s_nop 0
	global_load_dwordx4 v[178:181], v[178:179], off offset:576
	v_lshlrev_b64 v[222:223], 13, v[182:183]
	v_or_b32_e32 v140, 48, v140
	v_lshl_add_u64 v[202:203], v[142:143], 0, v[222:223]
	v_ashrrev_i32_e32 v141, 31, v140
	global_load_dwordx4 v[182:185], v[202:203], off
	global_load_dwordx4 v[194:197], v[202:203], off offset:64
	global_load_dwordx4 v[198:201], v[202:203], off offset:512
	s_nop 0
	global_load_dwordx4 v[202:205], v[202:203], off offset:576
	v_lshlrev_b64 v[140:141], 13, v[140:141]
	v_lshl_add_u64 v[240:241], v[142:143], 0, v[140:141]
	global_load_dwordx4 v[206:209], v[240:241], off
	global_load_dwordx4 v[210:213], v[240:241], off offset:64
	global_load_dwordx4 v[236:239], v[240:241], off offset:512
	s_nop 0
	global_load_dwordx4 v[240:243], v[240:241], off offset:576
	s_mov_b64 s[16:17], 0x100000
	s_and_b64 vcc, exec, s[10:11]
	s_mov_b32 s35, s34
	s_mov_b32 s36, s31
	s_mov_b64 s[18:19], s[14:15]
	v_readlane_b32 s22, v254, 48
	v_readlane_b32 s23, v254, 49
	s_waitcnt vmcnt(0)
	v_pk_fma_f32 v[126:127], v[126:127], 0.5, v[146:147] op_sel_hi:[1,0,1]
	v_lshl_add_u64 v[146:147], s[20:21], 0, v[144:145]
	v_lshl_add_u64 v[146:147], v[146:147], 0, v[138:139]
	v_pk_fma_f32 v[112:113], v[112:113], 0.5, v[160:161] op_sel_hi:[1,0,1]
	v_pk_fma_f32 v[110:111], v[110:111], 0.5, v[158:159] op_sel_hi:[1,0,1]
	global_store_dwordx4 v[146:147], v[110:113], off offset:512
	v_pk_fma_f32 v[104:105], v[104:105], 0.5, v[164:165] op_sel_hi:[1,0,1]
	v_pk_fma_f32 v[96:97], v[96:97], 0.5, v[176:177] op_sel_hi:[1,0,1]
	v_lshl_add_u64 v[110:111], s[20:21], 0, v[220:221]
	v_lshl_add_u64 v[110:111], v[110:111], 0, v[138:139]
	v_pk_fma_f32 v[94:95], v[94:95], 0.5, v[174:175] op_sel_hi:[1,0,1]
	global_store_dwordx4 v[110:111], v[94:97], off offset:512
	v_pk_fma_f32 v[80:81], v[80:81], 0.5, v[200:201] op_sel_hi:[1,0,1]
	v_pk_fma_f32 v[78:79], v[78:79], 0.5, v[198:199] op_sel_hi:[1,0,1]
	v_lshl_add_u64 v[94:95], s[20:21], 0, v[222:223]
	v_lshl_add_u64 v[94:95], v[94:95], 0, v[138:139]
	v_pk_fma_f32 v[102:103], v[102:103], 0.5, v[162:163] op_sel_hi:[1,0,1]
	v_pk_fma_f32 v[88:89], v[88:89], 0.5, v[180:181] op_sel_hi:[1,0,1]
	v_pk_fma_f32 v[86:87], v[86:87], 0.5, v[178:179] op_sel_hi:[1,0,1]
	global_store_dwordx4 v[94:95], v[78:81], off offset:512
	v_pk_fma_f32 v[76:77], v[76:77], 0.5, v[204:205] op_sel_hi:[1,0,1]
	v_pk_fma_f32 v[74:75], v[74:75], 0.5, v[202:203] op_sel_hi:[1,0,1]
	v_lshl_add_u64 v[78:79], s[20:21], 0, v[140:141]
	global_store_dwordx4 v[146:147], v[102:105], off offset:576
	global_store_dwordx4 v[110:111], v[86:89], off offset:576
	global_store_dwordx4 v[94:95], v[74:77], off offset:576
	v_pk_fma_f32 v[104:105], v[120:121], 0.5, v[168:169] op_sel_hi:[1,0,1]
	v_pk_fma_f32 v[102:103], v[118:119], 0.5, v[166:167] op_sel_hi:[1,0,1]
	v_pk_fma_f32 v[88:89], v[108:109], 0.5, v[184:185] op_sel_hi:[1,0,1]
	v_pk_fma_f32 v[86:87], v[106:107], 0.5, v[182:183] op_sel_hi:[1,0,1]
	v_pk_fma_f32 v[76:77], v[92:93], 0.5, v[208:209] op_sel_hi:[1,0,1]
	v_pk_fma_f32 v[74:75], v[90:91], 0.5, v[206:207] op_sel_hi:[1,0,1]
	v_lshl_add_u64 v[78:79], v[78:79], 0, v[138:139]
	v_pk_fma_f32 v[128:129], v[128:129], 0.5, v[148:149] op_sel_hi:[1,0,1]
	v_pk_fma_f32 v[124:125], v[124:125], 0.5, v[156:157] op_sel_hi:[1,0,1]
	v_pk_fma_f32 v[122:123], v[122:123], 0.5, v[154:155] op_sel_hi:[1,0,1]
	global_store_dwordx4 v[110:111], v[102:105], off
	global_store_dwordx4 v[94:95], v[86:89], off
	global_store_dwordx4 v[78:79], v[74:77], off
	v_pk_fma_f32 v[104:105], v[116:117], 0.5, v[172:173] op_sel_hi:[1,0,1]
	v_pk_fma_f32 v[102:103], v[114:115], 0.5, v[170:171] op_sel_hi:[1,0,1]
	v_pk_fma_f32 v[88:89], v[100:101], 0.5, v[196:197] op_sel_hi:[1,0,1]
	v_pk_fma_f32 v[86:87], v[98:99], 0.5, v[194:195] op_sel_hi:[1,0,1]
	v_pk_fma_f32 v[76:77], v[84:85], 0.5, v[212:213] op_sel_hi:[1,0,1]
	v_pk_fma_f32 v[74:75], v[82:83], 0.5, v[210:211] op_sel_hi:[1,0,1]
	v_pk_fma_f32 v[72:73], v[72:73], 0.5, v[238:239] op_sel_hi:[1,0,1]
	v_pk_fma_f32 v[70:71], v[70:71], 0.5, v[236:237] op_sel_hi:[1,0,1]
	v_pk_fma_f32 v[68:69], v[68:69], 0.5, v[242:243] op_sel_hi:[1,0,1]
	v_pk_fma_f32 v[66:67], v[66:67], 0.5, v[240:241] op_sel_hi:[1,0,1]
	v_lshl_add_u64 v[140:141], v[144:145], 0, s[16:17]
	global_store_dwordx4 v[146:147], v[126:129], off
	global_store_dwordx4 v[146:147], v[122:125], off offset:64
	global_store_dwordx4 v[110:111], v[102:105], off offset:64
	global_store_dwordx4 v[94:95], v[86:89], off offset:64
	global_store_dwordx4 v[78:79], v[74:77], off offset:64
	global_store_dwordx4 v[78:79], v[70:73], off offset:512
	global_store_dwordx4 v[78:79], v[66:69], off offset:576
	s_mov_b64 s[16:17], 0x120000
	v_lshl_add_u64 v[148:149], v[144:145], 0, s[16:17]
	v_lshl_add_u64 v[66:67], v[142:143], 0, v[140:141]
	global_load_dwordx4 v[78:81], v[66:67], off
	global_load_dwordx4 v[74:77], v[66:67], off offset:64
	global_load_dwordx4 v[70:73], v[66:67], off offset:512
	s_nop 0
	global_load_dwordx4 v[66:69], v[66:67], off offset:576
	v_lshl_add_u64 v[82:83], v[142:143], 0, v[148:149]
	s_mov_b64 s[16:17], 0x140000
	global_load_dwordx4 v[110:113], v[82:83], off
	global_load_dwordx4 v[106:109], v[82:83], off offset:64
	global_load_dwordx4 v[98:101], v[82:83], off offset:512
	global_load_dwordx4 v[90:93], v[82:83], off offset:576
	v_lshl_add_u64 v[146:147], v[144:145], 0, s[16:17]
	s_mov_b64 s[16:17], 0x160000
	v_lshl_add_u64 v[82:83], v[142:143], 0, v[146:147]
	v_lshl_add_u64 v[144:145], v[144:145], 0, s[16:17]
	global_load_dwordx4 v[102:105], v[82:83], off
	global_load_dwordx4 v[94:97], v[82:83], off offset:64
	global_load_dwordx4 v[86:89], v[82:83], off offset:512
	s_nop 0
	global_load_dwordx4 v[82:85], v[82:83], off offset:576
	v_lshl_add_u64 v[126:127], v[142:143], 0, v[144:145]
	global_load_dwordx4 v[118:121], v[126:127], off
	global_load_dwordx4 v[122:125], v[126:127], off offset:64
	global_load_dwordx4 v[114:117], v[126:127], off offset:512
	s_nop 0
	global_load_dwordx4 v[126:129], v[126:127], off offset:576
	s_mov_b64 s[16:17], s[12:13]
	s_waitcnt vmcnt(0)
	v_pk_fma_f32 v[62:63], v[62:63], 0.5, v[78:79] op_sel_hi:[1,0,1]
	v_lshl_add_u64 v[78:79], s[20:21], 0, v[140:141]
	v_lshl_add_u64 v[78:79], v[78:79], 0, v[138:139]
	v_pk_fma_f32 v[52:53], v[52:53], 0.5, v[72:73] op_sel_hi:[1,0,1]
	v_pk_fma_f32 v[50:51], v[50:51], 0.5, v[70:71] op_sel_hi:[1,0,1]
	global_store_dwordx4 v[78:79], v[50:53], off offset:512
	v_pk_fma_f32 v[36:37], v[36:37], 0.5, v[100:101] op_sel_hi:[1,0,1]
	v_pk_fma_f32 v[34:35], v[34:35], 0.5, v[98:99] op_sel_hi:[1,0,1]
	v_lshl_add_u64 v[50:51], s[20:21], 0, v[148:149]
	v_lshl_add_u64 v[50:51], v[50:51], 0, v[138:139]
	global_store_dwordx4 v[50:51], v[34:37], off offset:512
	v_pk_fma_f32 v[44:45], v[44:45], 0.5, v[68:69] op_sel_hi:[1,0,1]
	v_pk_fma_f32 v[42:43], v[42:43], 0.5, v[66:67] op_sel_hi:[1,0,1]
	v_lshl_add_u64 v[34:35], s[20:21], 0, v[146:147]
	v_pk_fma_f32 v[28:29], v[28:29], 0.5, v[92:93] op_sel_hi:[1,0,1]
	v_pk_fma_f32 v[26:27], v[26:27], 0.5, v[90:91] op_sel_hi:[1,0,1]
	v_lshl_add_u64 v[34:35], v[34:35], 0, v[138:139]
	v_pk_fma_f32 v[20:21], v[20:21], 0.5, v[88:89] op_sel_hi:[1,0,1]
	v_pk_fma_f32 v[18:19], v[18:19], 0.5, v[86:87] op_sel_hi:[1,0,1]
	global_store_dwordx4 v[78:79], v[42:45], off offset:576
	global_store_dwordx4 v[50:51], v[26:29], off offset:576
	global_store_dwordx4 v[34:35], v[18:21], off offset:512
	v_pk_fma_f32 v[44:45], v[56:57], 0.5, v[112:113] op_sel_hi:[1,0,1]
	v_pk_fma_f32 v[42:43], v[54:55], 0.5, v[110:111] op_sel_hi:[1,0,1]
	v_pk_fma_f32 v[28:29], v[40:41], 0.5, v[104:105] op_sel_hi:[1,0,1]
	v_pk_fma_f32 v[26:27], v[38:39], 0.5, v[102:103] op_sel_hi:[1,0,1]
	v_pk_fma_f32 v[16:17], v[16:17], 0.5, v[84:85] op_sel_hi:[1,0,1]
	v_pk_fma_f32 v[14:15], v[14:15], 0.5, v[82:83] op_sel_hi:[1,0,1]
	v_lshl_add_u64 v[18:19], s[20:21], 0, v[144:145]
	v_pk_fma_f32 v[64:65], v[64:65], 0.5, v[80:81] op_sel_hi:[1,0,1]
	v_pk_fma_f32 v[60:61], v[60:61], 0.5, v[76:77] op_sel_hi:[1,0,1]
	v_pk_fma_f32 v[58:59], v[58:59], 0.5, v[74:75] op_sel_hi:[1,0,1]
	global_store_dwordx4 v[50:51], v[42:45], off
	global_store_dwordx4 v[34:35], v[26:29], off
	global_store_dwordx4 v[34:35], v[14:17], off offset:576
	v_pk_fma_f32 v[44:45], v[48:49], 0.5, v[108:109] op_sel_hi:[1,0,1]
	v_pk_fma_f32 v[42:43], v[46:47], 0.5, v[106:107] op_sel_hi:[1,0,1]
	v_pk_fma_f32 v[28:29], v[32:33], 0.5, v[96:97] op_sel_hi:[1,0,1]
	v_pk_fma_f32 v[26:27], v[30:31], 0.5, v[94:95] op_sel_hi:[1,0,1]
	v_pk_fma_f32 v[16:17], v[24:25], 0.5, v[120:121] op_sel_hi:[1,0,1]
	v_pk_fma_f32 v[14:15], v[22:23], 0.5, v[118:119] op_sel_hi:[1,0,1]
	v_lshl_add_u64 v[18:19], v[18:19], 0, v[138:139]
	v_pk_fma_f32 v[12:13], v[12:13], 0.5, v[124:125] op_sel_hi:[1,0,1]
	v_pk_fma_f32 v[10:11], v[10:11], 0.5, v[122:123] op_sel_hi:[1,0,1]
	v_pk_fma_f32 v[8:9], v[8:9], 0.5, v[116:117] op_sel_hi:[1,0,1]
	v_pk_fma_f32 v[6:7], v[6:7], 0.5, v[114:115] op_sel_hi:[1,0,1]
	v_pk_fma_f32 v[4:5], v[4:5], 0.5, v[128:129] op_sel_hi:[1,0,1]
	v_pk_fma_f32 v[2:3], v[2:3], 0.5, v[126:127] op_sel_hi:[1,0,1]
	global_store_dwordx4 v[78:79], v[62:65], off
	global_store_dwordx4 v[78:79], v[58:61], off offset:64
	global_store_dwordx4 v[50:51], v[42:45], off offset:64
	global_store_dwordx4 v[34:35], v[26:29], off offset:64
	global_store_dwordx4 v[18:19], v[14:17], off
	global_store_dwordx4 v[18:19], v[10:13], off offset:64
	global_store_dwordx4 v[18:19], v[6:9], off offset:512
	global_store_dwordx4 v[18:19], v[2:5], off offset:576
	s_cbranch_vccz .LBB0_721
	s_waitcnt vmcnt(0)
	s_cmpk_gt_u32 s4, 0xff
	s_cbranch_scc1 .LBB0_736
	s_barrier

.LBB0_751:
	s_add_u32 s24, s12, 0xfff80080
	s_addc_u32 s25, s13, -1
	s_add_i32 s49, 0, 0x10000
	v_add_u32_e32 v148, s49, v1
	ds_read_b128 v[144:147], v148
	ds_read_b128 v[158:161], v148 offset:1024
	ds_read_b128 v[162:165], v148 offset:2048
	ds_read_b128 v[166:169], v148 offset:3072
	s_cmp_eq_u32 s48, 28
	s_cselect_b32 s27, s19, s25
	s_cselect_b32 s26, s44, s24
	s_cselect_b32 s25, s17, s47
	s_cselect_b32 s24, s45, s46
	v_lshl_add_u64 v[210:211], s[12:13], 0, v[140:141]
	s_add_i32 m0, s39, 0xc000
	ds_read_b128 v[170:173], v156
	ds_read_b128 v[174:177], v156 offset:1024
	ds_read_b128 v[178:181], v156 offset:2048
	ds_read_b128 v[182:185], v156 offset:3072
	ds_read_b128 v[194:197], v156 offset:4096
	ds_read_b128 v[198:201], v156 offset:5120
	ds_read_b128 v[202:205], v156 offset:6144
	ds_read_b128 v[206:209], v156 offset:7168
	global_load_lds_dwordx4 v[210:211], off
	v_lshl_add_u64 v[210:211], s[12:13], 0, v[142:143]
	s_add_i32 m0, s39, 0xe000
	s_nop 0
	global_load_lds_dwordx4 v[210:211], off
	s_waitcnt lgkmcnt(8)
	s_barrier
	s_waitcnt lgkmcnt(3)
	s_setprio 1
	v_mfma_f32_16x16x32_bf16 v[126:129], v[144:147], v[170:173], v[126:129]
	v_mfma_f32_16x16x32_bf16 v[118:121], v[162:165], v[170:173], v[118:121]
	v_mfma_f32_16x16x32_bf16 v[110:113], v[144:147], v[178:181], v[110:113]
	v_mfma_f32_16x16x32_bf16 v[102:105], v[162:165], v[178:181], v[102:105]
	v_mfma_f32_16x16x32_bf16 v[94:97], v[144:147], v[194:197], v[94:97]
	v_mfma_f32_16x16x32_bf16 v[86:89], v[162:165], v[194:197], v[86:89]
	s_waitcnt lgkmcnt(0)
	v_mfma_f32_16x16x32_bf16 v[78:81], v[144:147], v[202:205], v[78:81]
	v_mfma_f32_16x16x32_bf16 v[70:73], v[162:165], v[202:205], v[70:73]
	v_mfma_f32_16x16x32_bf16 v[126:129], v[158:161], v[174:177], v[126:129]
	v_mfma_f32_16x16x32_bf16 v[118:121], v[166:169], v[174:177], v[118:121]
	v_mfma_f32_16x16x32_bf16 v[110:113], v[158:161], v[182:185], v[110:113]
	v_mfma_f32_16x16x32_bf16 v[102:105], v[166:169], v[182:185], v[102:105]
	v_mfma_f32_16x16x32_bf16 v[94:97], v[158:161], v[198:201], v[94:97]
	v_mfma_f32_16x16x32_bf16 v[86:89], v[166:169], v[198:201], v[86:89]
	v_mfma_f32_16x16x32_bf16 v[78:81], v[158:161], v[206:209], v[78:81]
	v_mfma_f32_16x16x32_bf16 v[70:73], v[166:169], v[206:209], v[70:73]
	s_setprio 0
	s_barrier
	s_add_i32 s52, 0, 0x14000
	s_add_i32 s49, s49, s34
	v_add_u32_e32 v148, s52, v1
	v_lshl_add_u64 v[220:221], s[24:25], 0, v[134:135]
	s_mov_b32 m0, s49
	ds_read_b128 v[210:213], v148
	ds_read_b128 v[236:239], v148 offset:1024
	ds_read_b128 v[240:243], v148 offset:2048
	ds_read_b128 v[244:247], v148 offset:3072
	global_load_lds_dwordx4 v[220:221], off
	v_lshl_add_u64 v[222:223], s[24:25], 0, v[130:131]
	s_add_i32 m0, s49, 0x2000
	s_nop 0
	global_load_lds_dwordx4 v[222:223], off
	s_barrier
	s_waitcnt lgkmcnt(1)
	s_setprio 1
	v_mfma_f32_16x16x32_bf16 v[122:125], v[210:213], v[170:173], v[122:125]
	v_mfma_f32_16x16x32_bf16 v[114:117], v[240:243], v[170:173], v[114:117]
	v_mfma_f32_16x16x32_bf16 v[106:109], v[210:213], v[178:181], v[106:109]
	v_mfma_f32_16x16x32_bf16 v[98:101], v[240:243], v[178:181], v[98:101]
	v_mfma_f32_16x16x32_bf16 v[90:93], v[210:213], v[194:197], v[90:93]
	v_mfma_f32_16x16x32_bf16 v[82:85], v[240:243], v[194:197], v[82:85]
	s_waitcnt lgkmcnt(0)
	v_mfma_f32_16x16x32_bf16 v[74:77], v[210:213], v[202:205], v[74:77]
	v_mfma_f32_16x16x32_bf16 v[66:69], v[240:243], v[202:205], v[66:69]
	v_mfma_f32_16x16x32_bf16 v[122:125], v[236:239], v[174:177], v[122:125]
	v_mfma_f32_16x16x32_bf16 v[114:117], v[244:247], v[174:177], v[114:117]
	v_mfma_f32_16x16x32_bf16 v[106:109], v[236:239], v[182:185], v[106:109]
	v_mfma_f32_16x16x32_bf16 v[98:101], v[244:247], v[182:185], v[98:101]
	v_mfma_f32_16x16x32_bf16 v[90:93], v[236:239], v[198:201], v[90:93]
	v_mfma_f32_16x16x32_bf16 v[82:85], v[244:247], v[198:201], v[82:85]
	v_mfma_f32_16x16x32_bf16 v[74:77], v[236:239], v[206:209], v[74:77]
	v_mfma_f32_16x16x32_bf16 v[66:69], v[244:247], v[206:209], v[66:69]
	s_setprio 0
	s_mov_b32 m0, s39
	v_lshl_add_u64 v[248:249], s[26:27], 0, v[136:137]
	s_barrier
	ds_read_b128 v[170:173], v156 offset:16384
	ds_read_b128 v[174:177], v156 offset:17408
	ds_read_b128 v[178:181], v156 offset:18432
	ds_read_b128 v[182:185], v156 offset:19456
	ds_read_b128 v[194:197], v156 offset:20480
	ds_read_b128 v[198:201], v156 offset:21504
	ds_read_b128 v[202:205], v156 offset:22528
	ds_read_b128 v[206:209], v156 offset:23552
	global_load_lds_dwordx4 v[248:249], off
	v_lshl_add_u64 v[250:251], s[26:27], 0, v[132:133]
	s_mov_b32 m0, s40
	s_nop 0
	global_load_lds_dwordx4 v[250:251], off
	s_barrier
	s_waitcnt lgkmcnt(3)
	s_setprio 1
	v_mfma_f32_16x16x32_bf16 v[62:65], v[144:147], v[170:173], v[62:65]
	v_mfma_f32_16x16x32_bf16 v[54:57], v[162:165], v[170:173], v[54:57]
	v_mfma_f32_16x16x32_bf16 v[46:49], v[144:147], v[178:181], v[46:49]
	v_mfma_f32_16x16x32_bf16 v[38:41], v[162:165], v[178:181], v[38:41]
	v_mfma_f32_16x16x32_bf16 v[30:33], v[144:147], v[194:197], v[30:33]
	v_mfma_f32_16x16x32_bf16 v[22:25], v[162:165], v[194:197], v[22:25]
	s_waitcnt lgkmcnt(0)
	v_mfma_f32_16x16x32_bf16 v[14:17], v[144:147], v[202:205], v[14:17]
	v_mfma_f32_16x16x32_bf16 v[6:9], v[162:165], v[202:205], v[6:9]
	v_mfma_f32_16x16x32_bf16 v[62:65], v[158:161], v[174:177], v[62:65]
	v_mfma_f32_16x16x32_bf16 v[54:57], v[166:169], v[174:177], v[54:57]
	v_mfma_f32_16x16x32_bf16 v[46:49], v[158:161], v[182:185], v[46:49]
	v_mfma_f32_16x16x32_bf16 v[38:41], v[166:169], v[182:185], v[38:41]
	v_mfma_f32_16x16x32_bf16 v[30:33], v[158:161], v[198:201], v[30:33]
	v_mfma_f32_16x16x32_bf16 v[22:25], v[166:169], v[198:201], v[22:25]
	v_mfma_f32_16x16x32_bf16 v[14:17], v[158:161], v[206:209], v[14:17]
	v_mfma_f32_16x16x32_bf16 v[6:9], v[166:169], v[206:209], v[6:9]
	s_setprio 0
	s_barrier
	s_add_u32 s50, s24, 0x80000
	s_addc_u32 s51, s25, 0
	s_add_i32 s49, s52, s34
	v_lshl_add_u64 v[144:145], s[50:51], 0, v[134:135]
	s_mov_b32 m0, s49
	s_nop 0
	global_load_lds_dwordx4 v[144:145], off
	v_lshl_add_u64 v[144:145], s[50:51], 0, v[130:131]
	s_add_i32 m0, s49, 0x2000
	s_nop 0
	global_load_lds_dwordx4 v[144:145], off
	s_waitcnt vmcnt(6)
	s_barrier
	s_setprio 1
	v_mfma_f32_16x16x32_bf16 v[58:61], v[210:213], v[170:173], v[58:61]
	v_mfma_f32_16x16x32_bf16 v[50:53], v[240:243], v[170:173], v[50:53]
	v_mfma_f32_16x16x32_bf16 v[42:45], v[210:213], v[178:181], v[42:45]
	v_mfma_f32_16x16x32_bf16 v[34:37], v[240:243], v[178:181], v[34:37]
	v_mfma_f32_16x16x32_bf16 v[26:29], v[210:213], v[194:197], v[26:29]
	v_mfma_f32_16x16x32_bf16 v[18:21], v[240:243], v[194:197], v[18:21]
	v_mfma_f32_16x16x32_bf16 v[10:13], v[210:213], v[202:205], v[10:13]
	v_mfma_f32_16x16x32_bf16 v[2:5], v[240:243], v[202:205], v[2:5]
	v_mfma_f32_16x16x32_bf16 v[58:61], v[236:239], v[174:177], v[58:61]
	v_mfma_f32_16x16x32_bf16 v[50:53], v[244:247], v[174:177], v[50:53]
	v_mfma_f32_16x16x32_bf16 v[42:45], v[236:239], v[182:185], v[42:45]
	v_mfma_f32_16x16x32_bf16 v[34:37], v[244:247], v[182:185], v[34:37]
	v_mfma_f32_16x16x32_bf16 v[26:29], v[236:239], v[198:201], v[26:29]
	v_mfma_f32_16x16x32_bf16 v[18:21], v[244:247], v[198:201], v[18:21]
	v_mfma_f32_16x16x32_bf16 v[10:13], v[236:239], v[206:209], v[10:13]
	v_mfma_f32_16x16x32_bf16 v[2:5], v[244:247], v[206:209], v[2:5]
	s_setprio 0
	s_add_i32 s49, 0, 0x18000
	v_add_u32_e32 v148, s49, v1
	s_barrier
	ds_read_b128 v[144:147], v148
	ds_read_b128 v[158:161], v148 offset:1024
	ds_read_b128 v[162:165], v148 offset:2048
	ds_read_b128 v[166:169], v148 offset:3072
	s_add_u32 s26, s26, 0x80000
	s_addc_u32 s27, s27, 0
	s_mov_b32 m0, s41
	v_lshl_add_u64 v[210:211], s[26:27], 0, v[136:137]
	ds_read_b128 v[170:173], v156 offset:32768
	ds_read_b128 v[174:177], v156 offset:33792
	ds_read_b128 v[178:181], v156 offset:34816
	ds_read_b128 v[182:185], v156 offset:35840
	ds_read_b128 v[194:197], v156 offset:36864
	ds_read_b128 v[198:201], v156 offset:37888
	ds_read_b128 v[202:205], v156 offset:38912
	ds_read_b128 v[206:209], v156 offset:39936
	global_load_lds_dwordx4 v[210:211], off
	v_lshl_add_u64 v[210:211], s[26:27], 0, v[132:133]
	s_mov_b32 m0, s42
	s_nop 0
	global_load_lds_dwordx4 v[210:211], off
	s_waitcnt lgkmcnt(8)
	s_barrier
	s_waitcnt lgkmcnt(3)
	s_setprio 1
	v_mfma_f32_16x16x32_bf16 v[126:129], v[144:147], v[170:173], v[126:129]
	v_mfma_f32_16x16x32_bf16 v[118:121], v[162:165], v[170:173], v[118:121]
	v_mfma_f32_16x16x32_bf16 v[110:113], v[144:147], v[178:181], v[110:113]
	v_mfma_f32_16x16x32_bf16 v[102:105], v[162:165], v[178:181], v[102:105]
	v_mfma_f32_16x16x32_bf16 v[94:97], v[144:147], v[194:197], v[94:97]
	v_mfma_f32_16x16x32_bf16 v[86:89], v[162:165], v[194:197], v[86:89]
	s_waitcnt lgkmcnt(0)
	v_mfma_f32_16x16x32_bf16 v[78:81], v[144:147], v[202:205], v[78:81]
	v_mfma_f32_16x16x32_bf16 v[70:73], v[162:165], v[202:205], v[70:73]
	v_mfma_f32_16x16x32_bf16 v[126:129], v[158:161], v[174:177], v[126:129]
	v_mfma_f32_16x16x32_bf16 v[118:121], v[166:169], v[174:177], v[118:121]
	v_mfma_f32_16x16x32_bf16 v[110:113], v[158:161], v[182:185], v[110:113]
	v_mfma_f32_16x16x32_bf16 v[102:105], v[166:169], v[182:185], v[102:105]
	v_mfma_f32_16x16x32_bf16 v[94:97], v[158:161], v[198:201], v[94:97]
	v_mfma_f32_16x16x32_bf16 v[86:89], v[166:169], v[198:201], v[86:89]
	v_mfma_f32_16x16x32_bf16 v[78:81], v[158:161], v[206:209], v[78:81]
	v_mfma_f32_16x16x32_bf16 v[70:73], v[166:169], v[206:209], v[70:73]
	s_setprio 0
	s_barrier
	s_add_i32 s26, 0, 0x1c000
	s_add_i32 s27, s49, s34
	v_add_u32_e32 v148, s26, v1
	v_lshl_add_u64 v[220:221], v[220:221], 0, s[6:7]
	s_mov_b32 m0, s27
	ds_read_b128 v[210:213], v148
	ds_read_b128 v[236:239], v148 offset:1024
	ds_read_b128 v[240:243], v148 offset:2048
	ds_read_b128 v[244:247], v148 offset:3072
	global_load_lds_dwordx4 v[220:221], off
	v_lshl_add_u64 v[220:221], v[222:223], 0, s[6:7]
	s_add_i32 m0, s27, 0x2000
	s_nop 0
	global_load_lds_dwordx4 v[220:221], off
	s_barrier
	s_waitcnt lgkmcnt(1)
	s_setprio 1
	v_mfma_f32_16x16x32_bf16 v[122:125], v[210:213], v[170:173], v[122:125]
	v_mfma_f32_16x16x32_bf16 v[114:117], v[240:243], v[170:173], v[114:117]
	v_mfma_f32_16x16x32_bf16 v[106:109], v[210:213], v[178:181], v[106:109]
	v_mfma_f32_16x16x32_bf16 v[98:101], v[240:243], v[178:181], v[98:101]
	v_mfma_f32_16x16x32_bf16 v[90:93], v[210:213], v[194:197], v[90:93]
	v_mfma_f32_16x16x32_bf16 v[82:85], v[240:243], v[194:197], v[82:85]
	s_waitcnt lgkmcnt(0)
	v_mfma_f32_16x16x32_bf16 v[74:77], v[210:213], v[202:205], v[74:77]
	v_mfma_f32_16x16x32_bf16 v[66:69], v[240:243], v[202:205], v[66:69]
	v_mfma_f32_16x16x32_bf16 v[122:125], v[236:239], v[174:177], v[122:125]
	v_mfma_f32_16x16x32_bf16 v[114:117], v[244:247], v[174:177], v[114:117]
	v_mfma_f32_16x16x32_bf16 v[106:109], v[236:239], v[182:185], v[106:109]
	v_mfma_f32_16x16x32_bf16 v[98:101], v[244:247], v[182:185], v[98:101]
	v_mfma_f32_16x16x32_bf16 v[90:93], v[236:239], v[198:201], v[90:93]
	v_mfma_f32_16x16x32_bf16 v[82:85], v[244:247], v[198:201], v[82:85]
	v_mfma_f32_16x16x32_bf16 v[74:77], v[236:239], v[206:209], v[74:77]
	v_mfma_f32_16x16x32_bf16 v[66:69], v[244:247], v[206:209], v[66:69]
	s_setprio 0
	s_mov_b32 m0, s4
	v_lshl_add_u64 v[220:221], v[248:249], 0, s[6:7]
	s_barrier
	ds_read_b128 v[170:173], v156 offset:49152
	ds_read_b128 v[174:177], v156 offset:50176
	ds_read_b128 v[178:181], v156 offset:51200
	ds_read_b128 v[182:185], v156 offset:52224
	ds_read_b128 v[194:197], v156 offset:53248
	ds_read_b128 v[198:201], v156 offset:54272
	ds_read_b128 v[202:205], v156 offset:55296
	ds_read_b128 v[206:209], v156 offset:56320
	global_load_lds_dwordx4 v[220:221], off
	v_lshl_add_u64 v[220:221], v[250:251], 0, s[6:7]
	s_mov_b32 m0, s5
	s_nop 0
	global_load_lds_dwordx4 v[220:221], off
	s_barrier
	s_waitcnt lgkmcnt(3)
	s_setprio 1
	v_mfma_f32_16x16x32_bf16 v[62:65], v[144:147], v[170:173], v[62:65]
	v_mfma_f32_16x16x32_bf16 v[54:57], v[162:165], v[170:173], v[54:57]
	v_mfma_f32_16x16x32_bf16 v[46:49], v[144:147], v[178:181], v[46:49]
	v_mfma_f32_16x16x32_bf16 v[38:41], v[162:165], v[178:181], v[38:41]
	v_mfma_f32_16x16x32_bf16 v[30:33], v[144:147], v[194:197], v[30:33]
	v_mfma_f32_16x16x32_bf16 v[22:25], v[162:165], v[194:197], v[22:25]
	s_waitcnt lgkmcnt(0)
	v_mfma_f32_16x16x32_bf16 v[14:17], v[144:147], v[202:205], v[14:17]
	v_mfma_f32_16x16x32_bf16 v[6:9], v[162:165], v[202:205], v[6:9]
	v_mfma_f32_16x16x32_bf16 v[62:65], v[158:161], v[174:177], v[62:65]
	v_mfma_f32_16x16x32_bf16 v[54:57], v[166:169], v[174:177], v[54:57]
	v_mfma_f32_16x16x32_bf16 v[46:49], v[158:161], v[182:185], v[46:49]
	v_mfma_f32_16x16x32_bf16 v[38:41], v[166:169], v[182:185], v[38:41]
	v_mfma_f32_16x16x32_bf16 v[30:33], v[158:161], v[198:201], v[30:33]
	v_mfma_f32_16x16x32_bf16 v[22:25], v[166:169], v[198:201], v[22:25]
	v_mfma_f32_16x16x32_bf16 v[14:17], v[158:161], v[206:209], v[14:17]
	v_mfma_f32_16x16x32_bf16 v[6:9], v[166:169], v[206:209], v[6:9]
	s_setprio 0
	s_barrier
	s_add_u32 s24, s24, 0x80080
	s_addc_u32 s25, s25, 0
	s_add_i32 s26, s26, s34
	v_lshl_add_u64 v[144:145], s[24:25], 0, v[134:135]
	s_mov_b32 m0, s26
	s_nop 0
	global_load_lds_dwordx4 v[144:145], off
	v_lshl_add_u64 v[144:145], s[24:25], 0, v[130:131]
	s_add_i32 m0, s26, 0x2000
	s_nop 0
	global_load_lds_dwordx4 v[144:145], off
	s_waitcnt vmcnt(6)
	s_barrier
	s_setprio 1
	v_mfma_f32_16x16x32_bf16 v[58:61], v[210:213], v[170:173], v[58:61]
	v_mfma_f32_16x16x32_bf16 v[50:53], v[240:243], v[170:173], v[50:53]
	v_mfma_f32_16x16x32_bf16 v[42:45], v[210:213], v[178:181], v[42:45]
	v_mfma_f32_16x16x32_bf16 v[34:37], v[240:243], v[178:181], v[34:37]
	v_mfma_f32_16x16x32_bf16 v[26:29], v[210:213], v[194:197], v[26:29]
	v_mfma_f32_16x16x32_bf16 v[18:21], v[240:243], v[194:197], v[18:21]
	v_mfma_f32_16x16x32_bf16 v[10:13], v[210:213], v[202:205], v[10:13]
	v_mfma_f32_16x16x32_bf16 v[2:5], v[240:243], v[202:205], v[2:5]
	v_mfma_f32_16x16x32_bf16 v[58:61], v[236:239], v[174:177], v[58:61]
	v_mfma_f32_16x16x32_bf16 v[50:53], v[244:247], v[174:177], v[50:53]
	v_mfma_f32_16x16x32_bf16 v[42:45], v[236:239], v[182:185], v[42:45]
	v_mfma_f32_16x16x32_bf16 v[34:37], v[244:247], v[182:185], v[34:37]
	v_mfma_f32_16x16x32_bf16 v[26:29], v[236:239], v[198:201], v[26:29]
	v_mfma_f32_16x16x32_bf16 v[18:21], v[244:247], v[198:201], v[18:21]
	v_mfma_f32_16x16x32_bf16 v[10:13], v[236:239], v[206:209], v[10:13]
	v_mfma_f32_16x16x32_bf16 v[2:5], v[244:247], v[206:209], v[2:5]
	s_setprio 0
	s_add_i32 s48, s48, 2
	s_add_u32 s12, s12, 0x100
	s_addc_u32 s13, s13, 0
	s_add_u32 s46, s46, 0x100
	s_addc_u32 s47, s47, 0
	s_cmp_gt_u32 s48, 29
	s_barrier
	s_cbranch_scc0 .LBB0_751
	ds_read_b32 v160, v149
	ds_read_b32 v161, v149 offset:64
	ds_read_b32 v162, v149 offset:128
	ds_read_b32 v163, v150
	ds_read_b32 v164, v151
	ds_read_b32 v165, v152
	ds_read_b32 v166, v153
	ds_read_b32 v167, v154
	s_lshl_b32 s24, s29, 8
	s_cmp_lg_u32 s29, s30
	v_add_u32_e32 v144, s24, v138
	s_cselect_b64 s[26:27], -1, 0
	s_mov_b64 s[12:13], -1
	s_and_b64 vcc, exec, s[26:27]
	v_ashrrev_i32_e32 v145, 31, v144
	s_cbranch_vccz .LBB0_754
	v_lshl_add_u64 v[146:147], v[144:145], 2, s[14:15]
	global_load_dword v146, v[146:147], off
	s_mov_b64 s[12:13], 0
	s_waitcnt vmcnt(0)
	v_fmamk_f32 v146, v146, 0x3a000000, v215
	v_mul_f32_e32 v147, 0x4b800000, v146
	v_cmp_gt_f32_e32 vcc, s65, v146
	s_nop 1
	v_cndmask_b32_e32 v146, v146, v147, vcc
	v_rsq_f32_e32 v146, v146
	s_nop 0
	v_mul_f32_e32 v147, 0x45800000, v146
	v_cndmask_b32_e32 v148, v146, v147, vcc
